# V5 with every s_setprio removed from the GEMM K-loops (A/B of the per-block priority flips)
# speedup vs baseline: 1.0031x; 1.0031x over previous
; #define PG8_STAGE(bufoff, gbase, voff) do { _Pragma("unroll") for (int _i = 0; _i < 2; ++_i) \
;         __builtin_amdgcn_global_load_lds((const unsigned*)((const char*)(gbase) + (voff)[_i]), (PG8_LAS unsigned*)(lds + (bufoff) + ldsw + _i * 8192), 16, 0, 0); } while (0)
; #define PG8_LDA(dst, b, h) do { _Pragma("unroll") for (int m = 0; m < 4; ++m) _Pragma("unroll") for (int k = 0; k < 2; ++k) dst[m][k] = *(const PG8_LAS bf16x8*)(lds + PG8_SA(b, h) + aoff + m * 2048 + k * 1024); } while (0)
; #define PG8_LDB(dst, b, h) do { _Pragma("unroll") for (int n = 0; n < 2; ++n) _Pragma("unroll") for (int k = 0; k < 2; ++k) dst[n][k] = *(const PG8_LAS bf16x8*)(lds + PG8_SB(b, h) + boff + n * 2048 + k * 1024); } while (0)
; #define PG8_MMA(ai, bj, At, Bt) do { __builtin_amdgcn_s_setprio(1); _Pragma("unroll") for (int m = 0; m < 4; ++m) _Pragma("unroll") for (int n = 0; n < 2; ++n) _Pragma("unroll") for (int k = 0; k < 2; ++k) \
;         acc[ai][bj][m][n] = __builtin_amdgcn_mfma_f32_16x16x32_bf16(Bt[n][k], At[m][k], acc[ai][bj][m][n], 0, 0, 0); __builtin_amdgcn_s_setprio(0); } while (0)
; #define PG8_WAIT_V(n) asm volatile("s_waitcnt vmcnt(" #n ")" ::: "memory")
; #define PG8_WAIT_L(n) asm volatile("s_waitcnt lgkmcnt(" #n ")" ::: "memory")
; template <class Epi, class Sched, bool ALIGN_EPI = false, bool SP2 = false>
; __device__ __forceinline__ void gemm_phase(PG8_LAS unsigned char* lds, const Gemm g, const Sched& S, const Epi& E, int tid_in) {
;     ...
;             const bool last = (t == nt - 2);
;             const char* a1 = cA + (size_t)(t + 1) * kstep;
;             const char* a2 = last ? nA : cA + (size_t)(t + 2) * kstep; const char* b2 = last ? nB : cB + (size_t)(t + 2) * kstep;
;             const char* a3 = a2 + kstep; const char* b3 = b2 + kstep;
;             if (last && has_next) S.a_ready(nxt);
;             if constexpr (SP2) {
;             PG8_LDB(B0, 0, 0); PG8_LDB(B1, 0, 1); PG8_SCHED; PG8_LDA(At, 0, 0); PG8_STAGE(PG8_SA(1, 1), a1 + hstep, voffA);
;             PG8_WAIT_V(8); PG8_WAIT_L(0); PG8_BAR; PG8_MMA(0, 0, At, B0); PG8_MMA(0, 1, At, B1); PG8_BAR; PG8_SCHED;
;             PG8_LDA(At, 0, 1); PG8_STAGE(PG8_SB(0, 0), b2, voffB); PG8_STAGE(PG8_SB(0, 1), b2 + hstep, voffB); PG8_STAGE(PG8_SA(0, 0), a2, voffA);
;             PG8_WAIT_V(8); PG8_WAIT_L(0); PG8_BAR; PG8_MMA(1, 0, At, B0); PG8_MMA(1, 1, At, B1); PG8_BAR; PG8_SCHED;
.LBB0_376:
	s_add_u32 s26, s24, 0xfffc0080
	s_addc_u32 s27, s25, -1
	s_cmp_eq_u32 s56, 12
	s_cselect_b32 s29, s17, s27
	s_cselect_b32 s28, s52, s26
	s_cselect_b32 s27, s15, s55
	s_cselect_b32 s26, s53, s54
	s_add_i32 m0, s23, 0xc000
	ds_read_b128 v[150:153], v147
	global_load_lds_dwordx4 v136, s[24:25]
	s_add_i32 m0, s23, 0xe000
	ds_read_b128 v[154:157], v147 offset:1024
	global_load_lds_dwordx4 v138, s[24:25]
	ds_read_b128 v[158:161], v147 offset:2048
	ds_read_b128 v[162:165], v147 offset:3072
	ds_read_b128 v[166:169], v148
	ds_read_b128 v[170:173], v148 offset:1024
	ds_read_b128 v[174:177], v148 offset:2048
	ds_read_b128 v[178:181], v148 offset:3072
	ds_read_b128 v[182:185], v149
	ds_read_b128 v[186:189], v149 offset:1024
	ds_read_b128 v[190:193], v149 offset:2048
	ds_read_b128 v[194:197], v149 offset:3072
	ds_read_b128 v[198:201], v149 offset:4096
	ds_read_b128 v[202:205], v149 offset:5120
	ds_read_b128 v[206:209], v149 offset:6144
	ds_read_b128 v[210:213], v149 offset:7168
	s_waitcnt vmcnt(8)
	s_waitcnt lgkmcnt(0)
	s_barrier
	v_mfma_f32_16x16x32_bf16 v[124:127], v[150:153], v[182:185], v[124:127]
	v_mfma_f32_16x16x32_bf16 v[120:123], v[158:161], v[182:185], v[120:123]
	v_mfma_f32_16x16x32_bf16 v[108:111], v[150:153], v[190:193], v[108:111]
	v_mfma_f32_16x16x32_bf16 v[104:107], v[158:161], v[190:193], v[104:107]
	v_mfma_f32_16x16x32_bf16 v[92:95], v[150:153], v[198:201], v[92:95]
	v_mfma_f32_16x16x32_bf16 v[88:91], v[158:161], v[198:201], v[88:91]
	v_mfma_f32_16x16x32_bf16 v[76:79], v[150:153], v[206:209], v[76:79]
	v_mfma_f32_16x16x32_bf16 v[72:75], v[158:161], v[206:209], v[72:75]
	v_mfma_f32_16x16x32_bf16 v[124:127], v[154:157], v[186:189], v[124:127]
	v_mfma_f32_16x16x32_bf16 v[120:123], v[162:165], v[186:189], v[120:123]
	v_mfma_f32_16x16x32_bf16 v[108:111], v[154:157], v[194:197], v[108:111]
	v_mfma_f32_16x16x32_bf16 v[104:107], v[162:165], v[194:197], v[104:107]
	v_mfma_f32_16x16x32_bf16 v[92:95], v[154:157], v[202:205], v[92:95]
	v_mfma_f32_16x16x32_bf16 v[88:91], v[162:165], v[202:205], v[88:91]
	v_mfma_f32_16x16x32_bf16 v[76:79], v[154:157], v[210:213], v[76:79]
	v_mfma_f32_16x16x32_bf16 v[72:75], v[162:165], v[210:213], v[72:75]
	v_mfma_f32_16x16x32_bf16 v[116:119], v[166:169], v[182:185], v[116:119]
	v_mfma_f32_16x16x32_bf16 v[112:115], v[174:177], v[182:185], v[112:115]
	v_mfma_f32_16x16x32_bf16 v[100:103], v[166:169], v[190:193], v[100:103]
	v_mfma_f32_16x16x32_bf16 v[96:99], v[174:177], v[190:193], v[96:99]
	v_mfma_f32_16x16x32_bf16 v[84:87], v[166:169], v[198:201], v[84:87]
	v_mfma_f32_16x16x32_bf16 v[80:83], v[174:177], v[198:201], v[80:83]
	v_mfma_f32_16x16x32_bf16 v[68:71], v[166:169], v[206:209], v[68:71]
	v_mfma_f32_16x16x32_bf16 v[64:67], v[174:177], v[206:209], v[64:67]
	v_mfma_f32_16x16x32_bf16 v[116:119], v[170:173], v[186:189], v[116:119]
	v_mfma_f32_16x16x32_bf16 v[112:115], v[178:181], v[186:189], v[112:115]
	v_mfma_f32_16x16x32_bf16 v[100:103], v[170:173], v[194:197], v[100:103]
	v_mfma_f32_16x16x32_bf16 v[96:99], v[178:181], v[194:197], v[96:99]
	v_mfma_f32_16x16x32_bf16 v[84:87], v[170:173], v[202:205], v[84:87]
	v_mfma_f32_16x16x32_bf16 v[80:83], v[178:181], v[202:205], v[80:83]
	v_mfma_f32_16x16x32_bf16 v[68:71], v[170:173], v[210:213], v[68:71]
	v_mfma_f32_16x16x32_bf16 v[64:67], v[178:181], v[210:213], v[64:67]
	s_barrier
	s_add_u32 s98, s26, s10
	s_addc_u32 s99, s27, s11
	s_add_u32 s100, s28, s10
	s_addc_u32 s101, s29, s11
	s_add_i32 s57, s48, s34
	s_mov_b32 m0, s57
	ds_read_b128 v[182:185], v149 offset:16384
	global_load_lds_dwordx4 v132, s[26:27]
	s_add_i32 m0, s57, 0x2000
	s_add_u32 s60, s26, 0x40000
	s_addc_u32 s61, s27, 0
	s_add_i32 s57, s49, s34
	global_load_lds_dwordx4 v128, s[26:27]
	s_mov_b32 m0, s57
	ds_read_b128 v[186:189], v149 offset:17408
	global_load_lds_dwordx4 v132, s[60:61]
	s_add_i32 m0, s57, 0x2000
	ds_read_b128 v[190:193], v149 offset:18432
	global_load_lds_dwordx4 v128, s[60:61]
	s_mov_b32 m0, s23
	ds_read_b128 v[194:197], v149 offset:19456
	global_load_lds_dwordx4 v134, s[28:29]
	s_mov_b32 m0, s37
	ds_read_b128 v[198:201], v149 offset:20480
	global_load_lds_dwordx4 v130, s[28:29]
	ds_read_b128 v[202:205], v149 offset:21504
	ds_read_b128 v[206:209], v149 offset:22528
	ds_read_b128 v[210:213], v149 offset:23552
	s_waitcnt vmcnt(8)
	s_waitcnt lgkmcnt(0)
	s_barrier
	v_mfma_f32_16x16x32_bf16 v[60:63], v[150:153], v[182:185], v[60:63]
	v_mfma_f32_16x16x32_bf16 v[56:59], v[158:161], v[182:185], v[56:59]
	v_mfma_f32_16x16x32_bf16 v[44:47], v[150:153], v[190:193], v[44:47]
	v_mfma_f32_16x16x32_bf16 v[40:43], v[158:161], v[190:193], v[40:43]
	v_mfma_f32_16x16x32_bf16 v[28:31], v[150:153], v[198:201], v[28:31]
	v_mfma_f32_16x16x32_bf16 v[24:27], v[158:161], v[198:201], v[24:27]
	v_mfma_f32_16x16x32_bf16 v[12:15], v[150:153], v[206:209], v[12:15]
	v_mfma_f32_16x16x32_bf16 v[8:11], v[158:161], v[206:209], v[8:11]
	v_mfma_f32_16x16x32_bf16 v[60:63], v[154:157], v[186:189], v[60:63]
	v_mfma_f32_16x16x32_bf16 v[56:59], v[162:165], v[186:189], v[56:59]
	v_mfma_f32_16x16x32_bf16 v[44:47], v[154:157], v[194:197], v[44:47]
	v_mfma_f32_16x16x32_bf16 v[40:43], v[162:165], v[194:197], v[40:43]
	v_mfma_f32_16x16x32_bf16 v[28:31], v[154:157], v[202:205], v[28:31]
	v_mfma_f32_16x16x32_bf16 v[24:27], v[162:165], v[202:205], v[24:27]
	v_mfma_f32_16x16x32_bf16 v[12:15], v[154:157], v[210:213], v[12:15]
	v_mfma_f32_16x16x32_bf16 v[8:11], v[162:165], v[210:213], v[8:11]
	v_mfma_f32_16x16x32_bf16 v[52:55], v[166:169], v[182:185], v[52:55]
	v_mfma_f32_16x16x32_bf16 v[48:51], v[174:177], v[182:185], v[48:51]
	v_mfma_f32_16x16x32_bf16 v[36:39], v[166:169], v[190:193], v[36:39]
	v_mfma_f32_16x16x32_bf16 v[32:35], v[174:177], v[190:193], v[32:35]
	v_mfma_f32_16x16x32_bf16 v[20:23], v[166:169], v[198:201], v[20:23]
	v_mfma_f32_16x16x32_bf16 v[16:19], v[174:177], v[198:201], v[16:19]
	v_mfma_f32_16x16x32_bf16 v[4:7], v[166:169], v[206:209], v[4:7]
	v_mfma_f32_16x16x32_bf16 v[0:3], v[174:177], v[206:209], v[0:3]
	v_mfma_f32_16x16x32_bf16 v[52:55], v[170:173], v[186:189], v[52:55]
	v_mfma_f32_16x16x32_bf16 v[48:51], v[178:181], v[186:189], v[48:51]
	v_mfma_f32_16x16x32_bf16 v[36:39], v[170:173], v[194:197], v[36:39]
	v_mfma_f32_16x16x32_bf16 v[32:35], v[178:181], v[194:197], v[32:35]
	v_mfma_f32_16x16x32_bf16 v[20:23], v[170:173], v[202:205], v[20:23]
	v_mfma_f32_16x16x32_bf16 v[16:19], v[178:181], v[202:205], v[16:19]
	v_mfma_f32_16x16x32_bf16 v[4:7], v[170:173], v[210:213], v[4:7]
	v_mfma_f32_16x16x32_bf16 v[0:3], v[178:181], v[210:213], v[0:3]
	s_barrier
; #define PG8_STAGE(bufoff, gbase, voff) do { _Pragma("unroll") for (int _i = 0; _i < 2; ++_i) \
;         __builtin_amdgcn_global_load_lds((const unsigned*)((const char*)(gbase) + (voff)[_i]), (PG8_LAS unsigned*)(lds + (bufoff) + ldsw + _i * 8192), 16, 0, 0); } while (0)
; #define PG8_LDA(dst, b, h) do { _Pragma("unroll") for (int m = 0; m < 4; ++m) _Pragma("unroll") for (int k = 0; k < 2; ++k) dst[m][k] = *(const PG8_LAS bf16x8*)(lds + PG8_SA(b, h) + aoff + m * 2048 + k * 1024); } while (0)
; #define PG8_WAIT_V(n) asm volatile("s_waitcnt vmcnt(" #n ")" ::: "memory")
; template <class Epi, class Sched, bool ALIGN_EPI = false, bool SP2 = false>
; __device__ __forceinline__ void gemm_phase(PG8_LAS unsigned char* lds, const Gemm g, const Sched& S, const Epi& E, int tid_in) {
;     ...
;         for (int t = 0; t < nt; t += 2) {
;             if constexpr (Epi::MIDK) { if (t == Epi::MIDK_T) { if (wr == 0) PG8_BAR; E.mid(acc, cur, wr, wc, fr, fq); if (wr == 1) PG8_BAR; } }
;             const bool last = (t == nt - 2);
;             const char* a1 = cA + (size_t)(t + 1) * kstep;
;             const char* a2 = last ? nA : cA + (size_t)(t + 2) * kstep; const char* b2 = last ? nB : cB + (size_t)(t + 2) * kstep;
;             const char* a3 = a2 + kstep; const char* b3 = b2 + kstep;
;             if (last && has_next) S.a_ready(nxt);
;             if constexpr (SP2) {
;             PG8_LDB(B0, 0, 0); PG8_LDB(B1, 0, 1); PG8_SCHED; PG8_LDA(At, 0, 0); PG8_STAGE(PG8_SA(1, 1), a1 + hstep, voffA);
;             PG8_WAIT_V(8); PG8_WAIT_L(0); PG8_BAR; PG8_MMA(0, 0, At, B0); PG8_MMA(0, 1, At, B1); PG8_BAR; PG8_SCHED;
;             PG8_LDA(At, 0, 1); PG8_STAGE(PG8_SB(0, 0), b2, voffB); PG8_STAGE(PG8_SB(0, 1), b2 + hstep, voffB); PG8_STAGE(PG8_SA(0, 0), a2, voffA);
;             PG8_WAIT_V(8); PG8_WAIT_L(0); PG8_BAR; PG8_MMA(1, 0, At, B0); PG8_MMA(1, 1, At, B1); PG8_BAR; PG8_SCHED;
;             PG8_LDB(B0, 1, 0); PG8_LDB(B1, 1, 1); PG8_SCHED; PG8_LDA(At, 1, 0); PG8_STAGE(PG8_SA(0, 1), a2 + hstep, voffA);
;             PG8_WAIT_V(8); PG8_WAIT_L(0); PG8_BAR; PG8_MMA(0, 0, At, B0); PG8_MMA(0, 1, At, B1); PG8_BAR; PG8_SCHED;
;             PG8_LDA(At, 1, 1); PG8_STAGE(PG8_SB(1, 0), b3, voffB); PG8_STAGE(PG8_SB(1, 1), b3 + hstep, voffB); PG8_STAGE(PG8_SA(1, 0), a3, voffA);
;             PG8_WAIT_V(8); PG8_WAIT_L(0); PG8_BAR; PG8_MMA(1, 0, At, B0); PG8_MMA(1, 1, At, B1); PG8_BAR; PG8_SCHED;
	s_add_i32 s57, 0, 0x18000
	s_add_i32 s59, 0, 0x1c000
	s_add_u32 s28, s28, 0x40000
	s_addc_u32 s29, s29, 0
	s_mov_b32 m0, s38
	s_nop 0
	global_load_lds_dwordx4 v134, s[28:29]
	s_mov_b32 m0, s39
	s_nop 0
	global_load_lds_dwordx4 v130, s[28:29]
	v_add_u32_e32 v162, s57, v145
	v_add_u32_e32 v178, s59, v145
	ds_read_b128 v[150:153], v162
	ds_read_b128 v[154:157], v162 offset:1024
	ds_read_b128 v[158:161], v162 offset:2048
	ds_read_b128 v[162:165], v162 offset:3072
	ds_read_b128 v[166:169], v178
	ds_read_b128 v[170:173], v178 offset:1024
	ds_read_b128 v[174:177], v178 offset:2048
	ds_read_b128 v[178:181], v178 offset:3072
	ds_read_b128 v[182:185], v149 offset:32768
	ds_read_b128 v[186:189], v149 offset:33792
	ds_read_b128 v[190:193], v149 offset:34816
	ds_read_b128 v[194:197], v149 offset:35840
	ds_read_b128 v[198:201], v149 offset:36864
	ds_read_b128 v[202:205], v149 offset:37888
	ds_read_b128 v[206:209], v149 offset:38912
	ds_read_b128 v[210:213], v149 offset:39936
	s_waitcnt vmcnt(8)
	s_waitcnt lgkmcnt(0)
	s_barrier
	v_mfma_f32_16x16x32_bf16 v[124:127], v[150:153], v[182:185], v[124:127]
	v_mfma_f32_16x16x32_bf16 v[120:123], v[158:161], v[182:185], v[120:123]
	v_mfma_f32_16x16x32_bf16 v[108:111], v[150:153], v[190:193], v[108:111]
	v_mfma_f32_16x16x32_bf16 v[104:107], v[158:161], v[190:193], v[104:107]
	v_mfma_f32_16x16x32_bf16 v[92:95], v[150:153], v[198:201], v[92:95]
	v_mfma_f32_16x16x32_bf16 v[88:91], v[158:161], v[198:201], v[88:91]
	v_mfma_f32_16x16x32_bf16 v[76:79], v[150:153], v[206:209], v[76:79]
	v_mfma_f32_16x16x32_bf16 v[72:75], v[158:161], v[206:209], v[72:75]
	v_mfma_f32_16x16x32_bf16 v[124:127], v[154:157], v[186:189], v[124:127]
	v_mfma_f32_16x16x32_bf16 v[120:123], v[162:165], v[186:189], v[120:123]
	v_mfma_f32_16x16x32_bf16 v[108:111], v[154:157], v[194:197], v[108:111]
	v_mfma_f32_16x16x32_bf16 v[104:107], v[162:165], v[194:197], v[104:107]
	v_mfma_f32_16x16x32_bf16 v[92:95], v[154:157], v[202:205], v[92:95]
	v_mfma_f32_16x16x32_bf16 v[88:91], v[162:165], v[202:205], v[88:91]
	v_mfma_f32_16x16x32_bf16 v[76:79], v[154:157], v[210:213], v[76:79]
	v_mfma_f32_16x16x32_bf16 v[72:75], v[162:165], v[210:213], v[72:75]
	v_mfma_f32_16x16x32_bf16 v[116:119], v[166:169], v[182:185], v[116:119]
	v_mfma_f32_16x16x32_bf16 v[112:115], v[174:177], v[182:185], v[112:115]
	v_mfma_f32_16x16x32_bf16 v[100:103], v[166:169], v[190:193], v[100:103]
	v_mfma_f32_16x16x32_bf16 v[96:99], v[174:177], v[190:193], v[96:99]
	v_mfma_f32_16x16x32_bf16 v[84:87], v[166:169], v[198:201], v[84:87]
	v_mfma_f32_16x16x32_bf16 v[80:83], v[174:177], v[198:201], v[80:83]
	v_mfma_f32_16x16x32_bf16 v[68:71], v[166:169], v[206:209], v[68:71]
	v_mfma_f32_16x16x32_bf16 v[64:67], v[174:177], v[206:209], v[64:67]
	v_mfma_f32_16x16x32_bf16 v[116:119], v[170:173], v[186:189], v[116:119]
	v_mfma_f32_16x16x32_bf16 v[112:115], v[178:181], v[186:189], v[112:115]
	v_mfma_f32_16x16x32_bf16 v[100:103], v[170:173], v[194:197], v[100:103]
	v_mfma_f32_16x16x32_bf16 v[96:99], v[178:181], v[194:197], v[96:99]
	v_mfma_f32_16x16x32_bf16 v[84:87], v[170:173], v[202:205], v[84:87]
	v_mfma_f32_16x16x32_bf16 v[80:83], v[178:181], v[202:205], v[80:83]
	v_mfma_f32_16x16x32_bf16 v[68:71], v[170:173], v[210:213], v[68:71]
	v_mfma_f32_16x16x32_bf16 v[64:67], v[178:181], v[210:213], v[64:67]
	s_barrier
	s_add_i32 s28, s57, s34
	s_mov_b32 m0, s28
	ds_read_b128 v[182:185], v149 offset:49152
	global_load_lds_dwordx4 v132, s[98:99]
	s_add_i32 m0, s28, 0x2000
	s_add_u32 s26, s26, 0x40080
	s_addc_u32 s27, s27, 0
	s_add_i32 s28, s59, s34
	global_load_lds_dwordx4 v128, s[98:99]
	s_mov_b32 m0, s28
	ds_read_b128 v[186:189], v149 offset:50176
	global_load_lds_dwordx4 v132, s[26:27]
	s_add_i32 m0, s28, 0x2000
	ds_read_b128 v[190:193], v149 offset:51200
	global_load_lds_dwordx4 v128, s[26:27]
	s_mov_b32 m0, s44
	ds_read_b128 v[194:197], v149 offset:52224
	global_load_lds_dwordx4 v134, s[100:101]
	s_mov_b32 m0, s45
	ds_read_b128 v[198:201], v149 offset:53248
	global_load_lds_dwordx4 v130, s[100:101]
	ds_read_b128 v[202:205], v149 offset:54272
	ds_read_b128 v[206:209], v149 offset:55296
	ds_read_b128 v[210:213], v149 offset:56320
	s_waitcnt vmcnt(8)
	s_waitcnt lgkmcnt(0)
	s_barrier
	v_mfma_f32_16x16x32_bf16 v[60:63], v[150:153], v[182:185], v[60:63]
	v_mfma_f32_16x16x32_bf16 v[56:59], v[158:161], v[182:185], v[56:59]
	v_mfma_f32_16x16x32_bf16 v[44:47], v[150:153], v[190:193], v[44:47]
	v_mfma_f32_16x16x32_bf16 v[40:43], v[158:161], v[190:193], v[40:43]
	v_mfma_f32_16x16x32_bf16 v[28:31], v[150:153], v[198:201], v[28:31]
	v_mfma_f32_16x16x32_bf16 v[24:27], v[158:161], v[198:201], v[24:27]
	v_mfma_f32_16x16x32_bf16 v[12:15], v[150:153], v[206:209], v[12:15]
	v_mfma_f32_16x16x32_bf16 v[8:11], v[158:161], v[206:209], v[8:11]
	v_mfma_f32_16x16x32_bf16 v[60:63], v[154:157], v[186:189], v[60:63]
	v_mfma_f32_16x16x32_bf16 v[56:59], v[162:165], v[186:189], v[56:59]
	v_mfma_f32_16x16x32_bf16 v[44:47], v[154:157], v[194:197], v[44:47]
	v_mfma_f32_16x16x32_bf16 v[40:43], v[162:165], v[194:197], v[40:43]
	v_mfma_f32_16x16x32_bf16 v[28:31], v[154:157], v[202:205], v[28:31]
	v_mfma_f32_16x16x32_bf16 v[24:27], v[162:165], v[202:205], v[24:27]
	v_mfma_f32_16x16x32_bf16 v[12:15], v[154:157], v[210:213], v[12:15]
	v_mfma_f32_16x16x32_bf16 v[8:11], v[162:165], v[210:213], v[8:11]
	v_mfma_f32_16x16x32_bf16 v[52:55], v[166:169], v[182:185], v[52:55]
	v_mfma_f32_16x16x32_bf16 v[48:51], v[174:177], v[182:185], v[48:51]
	v_mfma_f32_16x16x32_bf16 v[36:39], v[166:169], v[190:193], v[36:39]
	v_mfma_f32_16x16x32_bf16 v[32:35], v[174:177], v[190:193], v[32:35]
	v_mfma_f32_16x16x32_bf16 v[20:23], v[166:169], v[198:201], v[20:23]
	v_mfma_f32_16x16x32_bf16 v[16:19], v[174:177], v[198:201], v[16:19]
	v_mfma_f32_16x16x32_bf16 v[4:7], v[166:169], v[206:209], v[4:7]
	v_mfma_f32_16x16x32_bf16 v[0:3], v[174:177], v[206:209], v[0:3]
	v_mfma_f32_16x16x32_bf16 v[52:55], v[170:173], v[186:189], v[52:55]
	v_mfma_f32_16x16x32_bf16 v[48:51], v[178:181], v[186:189], v[48:51]
	v_mfma_f32_16x16x32_bf16 v[36:39], v[170:173], v[194:197], v[36:39]
	v_mfma_f32_16x16x32_bf16 v[32:35], v[178:181], v[194:197], v[32:35]
	v_mfma_f32_16x16x32_bf16 v[20:23], v[170:173], v[202:205], v[20:23]
	v_mfma_f32_16x16x32_bf16 v[16:19], v[178:181], v[202:205], v[16:19]
	v_mfma_f32_16x16x32_bf16 v[4:7], v[170:173], v[210:213], v[4:7]
	v_mfma_f32_16x16x32_bf16 v[0:3], v[178:181], v[210:213], v[0:3]
	s_barrier
	s_add_i32 s56, s56, 2
	s_add_u32 s24, s24, 0x100
	s_addc_u32 s25, s25, 0
	s_add_u32 s54, s54, 0x100
	s_addc_u32 s55, s55, 0
	s_cmp_gt_u32 s56, 13
	s_cbranch_scc0 .LBB0_376
	s_and_b64 vcc, exec, s[12:13]
	s_cbranch_vccz .LBB0_379
	s_barrier

; #define PG8_STAGE(bufoff, gbase, voff) do { _Pragma("unroll") for (int _i = 0; _i < 2; ++_i) \
;         __builtin_amdgcn_global_load_lds((const unsigned*)((const char*)(gbase) + (voff)[_i]), (PG8_LAS unsigned*)(lds + (bufoff) + ldsw + _i * 8192), 16, 0, 0); } while (0)
; #define PG8_LDA(dst, b, h) do { _Pragma("unroll") for (int m = 0; m < 4; ++m) _Pragma("unroll") for (int k = 0; k < 2; ++k) dst[m][k] = *(const PG8_LAS bf16x8*)(lds + PG8_SA(b, h) + aoff + m * 2048 + k * 1024); } while (0)
; #define PG8_LDB(dst, b, h) do { _Pragma("unroll") for (int n = 0; n < 2; ++n) _Pragma("unroll") for (int k = 0; k < 2; ++k) dst[n][k] = *(const PG8_LAS bf16x8*)(lds + PG8_SB(b, h) + boff + n * 2048 + k * 1024); } while (0)
; #define PG8_WAIT_V(n) asm volatile("s_waitcnt vmcnt(" #n ")" ::: "memory")
; template <class Epi, class Sched, bool ALIGN_EPI = false, bool SP2 = false>
; __device__ __forceinline__ void gemm_phase(PG8_LAS unsigned char* lds, const Gemm g, const Sched& S, const Epi& E, int tid_in) {
;     ...
;             const char* a1 = cA + (size_t)(t + 1) * kstep;
;             const char* a2 = last ? nA : cA + (size_t)(t + 2) * kstep; const char* b2 = last ? nB : cB + (size_t)(t + 2) * kstep;
;             const char* a3 = a2 + kstep; const char* b3 = b2 + kstep;
;             if (last && has_next) S.a_ready(nxt);
;             if constexpr (SP2) {
;             PG8_LDB(B0, 0, 0); PG8_LDB(B1, 0, 1); PG8_SCHED; PG8_LDA(At, 0, 0); PG8_STAGE(PG8_SA(1, 1), a1 + hstep, voffA);
;             PG8_WAIT_V(8); PG8_WAIT_L(0); PG8_BAR; PG8_MMA(0, 0, At, B0); PG8_MMA(0, 1, At, B1); PG8_BAR; PG8_SCHED;
;             PG8_LDA(At, 0, 1); PG8_STAGE(PG8_SB(0, 0), b2, voffB); PG8_STAGE(PG8_SB(0, 1), b2 + hstep, voffB); PG8_STAGE(PG8_SA(0, 0), a2, voffA);
;             PG8_WAIT_V(8); PG8_WAIT_L(0); PG8_BAR; PG8_MMA(1, 0, At, B0); PG8_MMA(1, 1, At, B1); PG8_BAR; PG8_SCHED;
;             PG8_LDB(B0, 1, 0); PG8_LDB(B1, 1, 1); PG8_SCHED; PG8_LDA(At, 1, 0); PG8_STAGE(PG8_SA(0, 1), a2 + hstep, voffA);
;             PG8_WAIT_V(8); PG8_WAIT_L(0); PG8_BAR; PG8_MMA(0, 0, At, B0); PG8_MMA(0, 1, At, B1); PG8_BAR; PG8_SCHED;
;             PG8_LDA(At, 1, 1); PG8_STAGE(PG8_SB(1, 0), b3, voffB); PG8_STAGE(PG8_SB(1, 1), b3 + hstep, voffB); PG8_STAGE(PG8_SA(1, 0), a3, voffA);
;             PG8_WAIT_V(8); PG8_WAIT_L(0); PG8_BAR; PG8_MMA(1, 0, At, B0); PG8_MMA(1, 1, At, B1); PG8_BAR; PG8_SCHED;
.LBB0_461:
	s_add_u32 s6, s48, 0x100
	s_addc_u32 s7, s49, 0
	s_cmp_eq_u32 s76, 40
	s_cselect_b32 s53, s45, s7
	s_cselect_b32 s52, s44, s6
	s_cselect_b32 s51, s47, s75
	s_cselect_b32 s50, s46, s12
	s_add_i32 m0, s60, 0xc000
	ds_read_b128 v[128:131], v236
	global_load_lds_dwordx4 v200, s[48:49]
	s_add_i32 m0, s60, 0xe000
	ds_read_b128 v[132:135], v236 offset:1024
	global_load_lds_dwordx4 v202, s[48:49]
	ds_read_b128 v[136:139], v236 offset:2048
	ds_read_b128 v[140:143], v236 offset:3072
	ds_read_b128 v[144:147], v237
	ds_read_b128 v[148:151], v237 offset:1024
	ds_read_b128 v[152:155], v237 offset:2048
	ds_read_b128 v[156:159], v237 offset:3072
	ds_read_b128 v[160:163], v238
	ds_read_b128 v[164:167], v238 offset:1024
	ds_read_b128 v[168:171], v238 offset:2048
	ds_read_b128 v[172:175], v238 offset:3072
	ds_read_b128 v[176:179], v238 offset:4096
	ds_read_b128 v[180:183], v238 offset:5120
	ds_read_b128 v[184:187], v238 offset:6144
	ds_read_b128 v[188:191], v238 offset:7168
	s_waitcnt vmcnt(8)
	s_waitcnt lgkmcnt(0)
	s_barrier
	v_mfma_f32_16x16x32_bf16 v[124:127], v[128:131], v[160:163], v[124:127]
	v_mfma_f32_16x16x32_bf16 v[120:123], v[136:139], v[160:163], v[120:123]
	v_mfma_f32_16x16x32_bf16 v[108:111], v[128:131], v[168:171], v[108:111]
	v_mfma_f32_16x16x32_bf16 v[104:107], v[136:139], v[168:171], v[104:107]
	v_mfma_f32_16x16x32_bf16 v[92:95], v[128:131], v[176:179], v[92:95]
	v_mfma_f32_16x16x32_bf16 v[88:91], v[136:139], v[176:179], v[88:91]
	v_mfma_f32_16x16x32_bf16 v[76:79], v[128:131], v[184:187], v[76:79]
	v_mfma_f32_16x16x32_bf16 v[72:75], v[136:139], v[184:187], v[72:75]
	v_mfma_f32_16x16x32_bf16 v[124:127], v[132:135], v[164:167], v[124:127]
	v_mfma_f32_16x16x32_bf16 v[120:123], v[140:143], v[164:167], v[120:123]
	v_mfma_f32_16x16x32_bf16 v[108:111], v[132:135], v[172:175], v[108:111]
	v_mfma_f32_16x16x32_bf16 v[104:107], v[140:143], v[172:175], v[104:107]
	v_mfma_f32_16x16x32_bf16 v[92:95], v[132:135], v[180:183], v[92:95]
	v_mfma_f32_16x16x32_bf16 v[88:91], v[140:143], v[180:183], v[88:91]
	v_mfma_f32_16x16x32_bf16 v[76:79], v[132:135], v[188:191], v[76:79]
	v_mfma_f32_16x16x32_bf16 v[72:75], v[140:143], v[188:191], v[72:75]
	v_mfma_f32_16x16x32_bf16 v[116:119], v[144:147], v[160:163], v[116:119]
	v_mfma_f32_16x16x32_bf16 v[112:115], v[152:155], v[160:163], v[112:115]
	v_mfma_f32_16x16x32_bf16 v[100:103], v[144:147], v[168:171], v[100:103]
	v_mfma_f32_16x16x32_bf16 v[96:99], v[152:155], v[168:171], v[96:99]
	v_mfma_f32_16x16x32_bf16 v[84:87], v[144:147], v[176:179], v[84:87]
	v_mfma_f32_16x16x32_bf16 v[80:83], v[152:155], v[176:179], v[80:83]
	v_mfma_f32_16x16x32_bf16 v[68:71], v[144:147], v[184:187], v[68:71]
	v_mfma_f32_16x16x32_bf16 v[64:67], v[152:155], v[184:187], v[64:67]
	v_mfma_f32_16x16x32_bf16 v[116:119], v[148:151], v[164:167], v[116:119]
	v_mfma_f32_16x16x32_bf16 v[112:115], v[156:159], v[164:167], v[112:115]
	v_mfma_f32_16x16x32_bf16 v[100:103], v[148:151], v[172:175], v[100:103]
	v_mfma_f32_16x16x32_bf16 v[96:99], v[156:159], v[172:175], v[96:99]
	v_mfma_f32_16x16x32_bf16 v[84:87], v[148:151], v[180:183], v[84:87]
	v_mfma_f32_16x16x32_bf16 v[80:83], v[156:159], v[180:183], v[80:83]
	v_mfma_f32_16x16x32_bf16 v[68:71], v[148:151], v[188:191], v[68:71]
	v_mfma_f32_16x16x32_bf16 v[64:67], v[156:159], v[188:191], v[64:67]
	s_barrier
	s_add_u32 s98, s50, s22
	s_addc_u32 s99, s51, s23
	s_add_u32 s100, s52, s22
	s_addc_u32 s101, s53, s23
	s_add_i32 s48, s70, s59
	s_mov_b32 m0, s48
	ds_read_b128 v[160:163], v238 offset:16384
	global_load_lds_dwordx4 v194, s[50:51]
	s_add_i32 m0, s48, 0x2000
	s_add_u32 s48, s50, 0xb0000
	s_addc_u32 s49, s51, 0
	s_add_i32 s77, s71, s59
	global_load_lds_dwordx4 v198, s[50:51]
	s_mov_b32 m0, s77
	ds_read_b128 v[164:167], v238 offset:17408
	global_load_lds_dwordx4 v194, s[48:49]
	s_add_i32 m0, s77, 0x2000
	ds_read_b128 v[168:171], v238 offset:18432
	global_load_lds_dwordx4 v198, s[48:49]
	s_mov_b32 m0, s60
	ds_read_b128 v[172:175], v238 offset:19456
	global_load_lds_dwordx4 v192, s[52:53]
	s_mov_b32 m0, s61
	ds_read_b128 v[176:179], v238 offset:20480
	global_load_lds_dwordx4 v196, s[52:53]
	ds_read_b128 v[180:183], v238 offset:21504
	ds_read_b128 v[184:187], v238 offset:22528
	ds_read_b128 v[188:191], v238 offset:23552
	s_waitcnt vmcnt(8)
	s_waitcnt lgkmcnt(0)
	s_barrier
	v_mfma_f32_16x16x32_bf16 v[60:63], v[128:131], v[160:163], v[60:63]
	v_mfma_f32_16x16x32_bf16 v[56:59], v[136:139], v[160:163], v[56:59]
	v_mfma_f32_16x16x32_bf16 v[44:47], v[128:131], v[168:171], v[44:47]
	v_mfma_f32_16x16x32_bf16 v[40:43], v[136:139], v[168:171], v[40:43]
	v_mfma_f32_16x16x32_bf16 v[28:31], v[128:131], v[176:179], v[28:31]
	v_mfma_f32_16x16x32_bf16 v[24:27], v[136:139], v[176:179], v[24:27]
	v_mfma_f32_16x16x32_bf16 v[12:15], v[128:131], v[184:187], v[12:15]
	v_mfma_f32_16x16x32_bf16 v[8:11], v[136:139], v[184:187], v[8:11]
	v_mfma_f32_16x16x32_bf16 v[60:63], v[132:135], v[164:167], v[60:63]
	v_mfma_f32_16x16x32_bf16 v[56:59], v[140:143], v[164:167], v[56:59]
	v_mfma_f32_16x16x32_bf16 v[44:47], v[132:135], v[172:175], v[44:47]
	v_mfma_f32_16x16x32_bf16 v[40:43], v[140:143], v[172:175], v[40:43]
	v_mfma_f32_16x16x32_bf16 v[28:31], v[132:135], v[180:183], v[28:31]
	v_mfma_f32_16x16x32_bf16 v[24:27], v[140:143], v[180:183], v[24:27]
	v_mfma_f32_16x16x32_bf16 v[12:15], v[132:135], v[188:191], v[12:15]
	v_mfma_f32_16x16x32_bf16 v[8:11], v[140:143], v[188:191], v[8:11]
	v_mfma_f32_16x16x32_bf16 v[52:55], v[144:147], v[160:163], v[52:55]
	v_mfma_f32_16x16x32_bf16 v[48:51], v[152:155], v[160:163], v[48:51]
	v_mfma_f32_16x16x32_bf16 v[36:39], v[144:147], v[168:171], v[36:39]
	v_mfma_f32_16x16x32_bf16 v[32:35], v[152:155], v[168:171], v[32:35]
	v_mfma_f32_16x16x32_bf16 v[20:23], v[144:147], v[176:179], v[20:23]
	v_mfma_f32_16x16x32_bf16 v[16:19], v[152:155], v[176:179], v[16:19]
	v_mfma_f32_16x16x32_bf16 v[4:7], v[144:147], v[184:187], v[4:7]
	v_mfma_f32_16x16x32_bf16 v[0:3], v[152:155], v[184:187], v[0:3]
	v_mfma_f32_16x16x32_bf16 v[52:55], v[148:151], v[164:167], v[52:55]
	v_mfma_f32_16x16x32_bf16 v[48:51], v[156:159], v[164:167], v[48:51]
	v_mfma_f32_16x16x32_bf16 v[36:39], v[148:151], v[172:175], v[36:39]
	v_mfma_f32_16x16x32_bf16 v[32:35], v[156:159], v[172:175], v[32:35]
	v_mfma_f32_16x16x32_bf16 v[20:23], v[148:151], v[180:183], v[20:23]
	v_mfma_f32_16x16x32_bf16 v[16:19], v[156:159], v[180:183], v[16:19]
	v_mfma_f32_16x16x32_bf16 v[4:7], v[148:151], v[188:191], v[4:7]
	v_mfma_f32_16x16x32_bf16 v[0:3], v[156:159], v[188:191], v[0:3]
	s_barrier
; #define PG8_STAGE(bufoff, gbase, voff) do { _Pragma("unroll") for (int _i = 0; _i < 2; ++_i) \
;         __builtin_amdgcn_global_load_lds((const unsigned*)((const char*)(gbase) + (voff)[_i]), (PG8_LAS unsigned*)(lds + (bufoff) + ldsw + _i * 8192), 16, 0, 0); } while (0)
; #define PG8_LDA(dst, b, h) do { _Pragma("unroll") for (int m = 0; m < 4; ++m) _Pragma("unroll") for (int k = 0; k < 2; ++k) dst[m][k] = *(const PG8_LAS bf16x8*)(lds + PG8_SA(b, h) + aoff + m * 2048 + k * 1024); } while (0)
; #define PG8_LDB(dst, b, h) do { _Pragma("unroll") for (int n = 0; n < 2; ++n) _Pragma("unroll") for (int k = 0; k < 2; ++k) dst[n][k] = *(const PG8_LAS bf16x8*)(lds + PG8_SB(b, h) + boff + n * 2048 + k * 1024); } while (0)
; #define PG8_WAIT_V(n) asm volatile("s_waitcnt vmcnt(" #n ")" ::: "memory")
; template <class Epi, class Sched, bool ALIGN_EPI = false, bool SP2 = false>
; __device__ __forceinline__ void gemm_phase(PG8_LAS unsigned char* lds, const Gemm g, const Sched& S, const Epi& E, int tid_in) {
;     ...
;             const char* a1 = cA + (size_t)(t + 1) * kstep;
;             const char* a2 = last ? nA : cA + (size_t)(t + 2) * kstep; const char* b2 = last ? nB : cB + (size_t)(t + 2) * kstep;
;             const char* a3 = a2 + kstep; const char* b3 = b2 + kstep;
;             if (last && has_next) S.a_ready(nxt);
;             if constexpr (SP2) {
;             PG8_LDB(B0, 0, 0); PG8_LDB(B1, 0, 1); PG8_SCHED; PG8_LDA(At, 0, 0); PG8_STAGE(PG8_SA(1, 1), a1 + hstep, voffA);
;             PG8_WAIT_V(8); PG8_WAIT_L(0); PG8_BAR; PG8_MMA(0, 0, At, B0); PG8_MMA(0, 1, At, B1); PG8_BAR; PG8_SCHED;
;             PG8_LDA(At, 0, 1); PG8_STAGE(PG8_SB(0, 0), b2, voffB); PG8_STAGE(PG8_SB(0, 1), b2 + hstep, voffB); PG8_STAGE(PG8_SA(0, 0), a2, voffA);
;             PG8_WAIT_V(8); PG8_WAIT_L(0); PG8_BAR; PG8_MMA(1, 0, At, B0); PG8_MMA(1, 1, At, B1); PG8_BAR; PG8_SCHED;
;             PG8_LDB(B0, 1, 0); PG8_LDB(B1, 1, 1); PG8_SCHED; PG8_LDA(At, 1, 0); PG8_STAGE(PG8_SA(0, 1), a2 + hstep, voffA);
;             PG8_WAIT_V(8); PG8_WAIT_L(0); PG8_BAR; PG8_MMA(0, 0, At, B0); PG8_MMA(0, 1, At, B1); PG8_BAR; PG8_SCHED;
;             PG8_LDA(At, 1, 1); PG8_STAGE(PG8_SB(1, 0), b3, voffB); PG8_STAGE(PG8_SB(1, 1), b3 + hstep, voffB); PG8_STAGE(PG8_SA(1, 0), a3, voffA);
;             PG8_WAIT_V(8); PG8_WAIT_L(0); PG8_BAR; PG8_MMA(1, 0, At, B0); PG8_MMA(1, 1, At, B1); PG8_BAR; PG8_SCHED;
	s_add_i32 s77, 0, 0x18000
	s_add_i32 s78, 0, 0x1c000
	s_add_u32 s48, s52, 0xb0000
	s_addc_u32 s49, s53, 0
	s_mov_b32 m0, s62
	s_nop 0
	global_load_lds_dwordx4 v192, s[48:49]
	s_mov_b32 m0, s63
	s_nop 0
	global_load_lds_dwordx4 v196, s[48:49]
	v_add_u32_e32 v140, s77, v232
	v_add_u32_e32 v156, s78, v232
	ds_read_b128 v[128:131], v140
	ds_read_b128 v[132:135], v140 offset:1024
	ds_read_b128 v[136:139], v140 offset:2048
	ds_read_b128 v[140:143], v140 offset:3072
	ds_read_b128 v[144:147], v156
	ds_read_b128 v[148:151], v156 offset:1024
	ds_read_b128 v[152:155], v156 offset:2048
	ds_read_b128 v[156:159], v156 offset:3072
	ds_read_b128 v[160:163], v238 offset:32768
	ds_read_b128 v[164:167], v238 offset:33792
	ds_read_b128 v[168:171], v238 offset:34816
	ds_read_b128 v[172:175], v238 offset:35840
	ds_read_b128 v[176:179], v238 offset:36864
	ds_read_b128 v[180:183], v238 offset:37888
	ds_read_b128 v[184:187], v238 offset:38912
	ds_read_b128 v[188:191], v238 offset:39936
	s_waitcnt vmcnt(8)
	s_waitcnt lgkmcnt(0)
	s_barrier
	v_mfma_f32_16x16x32_bf16 v[124:127], v[128:131], v[160:163], v[124:127]
	v_mfma_f32_16x16x32_bf16 v[120:123], v[136:139], v[160:163], v[120:123]
	v_mfma_f32_16x16x32_bf16 v[108:111], v[128:131], v[168:171], v[108:111]
	v_mfma_f32_16x16x32_bf16 v[104:107], v[136:139], v[168:171], v[104:107]
	v_mfma_f32_16x16x32_bf16 v[92:95], v[128:131], v[176:179], v[92:95]
	v_mfma_f32_16x16x32_bf16 v[88:91], v[136:139], v[176:179], v[88:91]
	v_mfma_f32_16x16x32_bf16 v[76:79], v[128:131], v[184:187], v[76:79]
	v_mfma_f32_16x16x32_bf16 v[72:75], v[136:139], v[184:187], v[72:75]
	v_mfma_f32_16x16x32_bf16 v[124:127], v[132:135], v[164:167], v[124:127]
	v_mfma_f32_16x16x32_bf16 v[120:123], v[140:143], v[164:167], v[120:123]
	v_mfma_f32_16x16x32_bf16 v[108:111], v[132:135], v[172:175], v[108:111]
	v_mfma_f32_16x16x32_bf16 v[104:107], v[140:143], v[172:175], v[104:107]
	v_mfma_f32_16x16x32_bf16 v[92:95], v[132:135], v[180:183], v[92:95]
	v_mfma_f32_16x16x32_bf16 v[88:91], v[140:143], v[180:183], v[88:91]
	v_mfma_f32_16x16x32_bf16 v[76:79], v[132:135], v[188:191], v[76:79]
	v_mfma_f32_16x16x32_bf16 v[72:75], v[140:143], v[188:191], v[72:75]
	v_mfma_f32_16x16x32_bf16 v[116:119], v[144:147], v[160:163], v[116:119]
	v_mfma_f32_16x16x32_bf16 v[112:115], v[152:155], v[160:163], v[112:115]
	v_mfma_f32_16x16x32_bf16 v[100:103], v[144:147], v[168:171], v[100:103]
	v_mfma_f32_16x16x32_bf16 v[96:99], v[152:155], v[168:171], v[96:99]
	v_mfma_f32_16x16x32_bf16 v[84:87], v[144:147], v[176:179], v[84:87]
	v_mfma_f32_16x16x32_bf16 v[80:83], v[152:155], v[176:179], v[80:83]
	v_mfma_f32_16x16x32_bf16 v[68:71], v[144:147], v[184:187], v[68:71]
	v_mfma_f32_16x16x32_bf16 v[64:67], v[152:155], v[184:187], v[64:67]
	v_mfma_f32_16x16x32_bf16 v[116:119], v[148:151], v[164:167], v[116:119]
	v_mfma_f32_16x16x32_bf16 v[112:115], v[156:159], v[164:167], v[112:115]
	v_mfma_f32_16x16x32_bf16 v[100:103], v[148:151], v[172:175], v[100:103]
	v_mfma_f32_16x16x32_bf16 v[96:99], v[156:159], v[172:175], v[96:99]
	v_mfma_f32_16x16x32_bf16 v[84:87], v[148:151], v[180:183], v[84:87]
	v_mfma_f32_16x16x32_bf16 v[80:83], v[156:159], v[180:183], v[80:83]
	v_mfma_f32_16x16x32_bf16 v[68:71], v[148:151], v[188:191], v[68:71]
	v_mfma_f32_16x16x32_bf16 v[64:67], v[156:159], v[188:191], v[64:67]
	s_barrier
	s_add_i32 s48, s77, s59
	s_mov_b32 m0, s48
	ds_read_b128 v[160:163], v238 offset:49152
	global_load_lds_dwordx4 v194, s[98:99]
	s_add_i32 m0, s48, 0x2000
	s_add_u32 s48, s50, 0xb0080
	s_addc_u32 s49, s51, 0
	s_add_i32 s50, s78, s59
	global_load_lds_dwordx4 v198, s[98:99]
	s_mov_b32 m0, s50
	ds_read_b128 v[164:167], v238 offset:50176
	global_load_lds_dwordx4 v194, s[48:49]
	s_add_i32 m0, s50, 0x2000
	ds_read_b128 v[168:171], v238 offset:51200
	global_load_lds_dwordx4 v198, s[48:49]
	s_mov_b32 m0, s65
	ds_read_b128 v[172:175], v238 offset:52224
	global_load_lds_dwordx4 v192, s[100:101]
	s_mov_b32 m0, s67
	ds_read_b128 v[176:179], v238 offset:53248
	global_load_lds_dwordx4 v196, s[100:101]
	ds_read_b128 v[180:183], v238 offset:54272
	ds_read_b128 v[184:187], v238 offset:55296
	ds_read_b128 v[188:191], v238 offset:56320
	s_waitcnt vmcnt(8)
	s_waitcnt lgkmcnt(0)
	s_barrier
	v_mfma_f32_16x16x32_bf16 v[60:63], v[128:131], v[160:163], v[60:63]
	v_mfma_f32_16x16x32_bf16 v[56:59], v[136:139], v[160:163], v[56:59]
	v_mfma_f32_16x16x32_bf16 v[44:47], v[128:131], v[168:171], v[44:47]
	v_mfma_f32_16x16x32_bf16 v[40:43], v[136:139], v[168:171], v[40:43]
	v_mfma_f32_16x16x32_bf16 v[28:31], v[128:131], v[176:179], v[28:31]
	v_mfma_f32_16x16x32_bf16 v[24:27], v[136:139], v[176:179], v[24:27]
	v_mfma_f32_16x16x32_bf16 v[12:15], v[128:131], v[184:187], v[12:15]
	v_mfma_f32_16x16x32_bf16 v[8:11], v[136:139], v[184:187], v[8:11]
	v_mfma_f32_16x16x32_bf16 v[60:63], v[132:135], v[164:167], v[60:63]
	v_mfma_f32_16x16x32_bf16 v[56:59], v[140:143], v[164:167], v[56:59]
	v_mfma_f32_16x16x32_bf16 v[44:47], v[132:135], v[172:175], v[44:47]
	v_mfma_f32_16x16x32_bf16 v[40:43], v[140:143], v[172:175], v[40:43]
	v_mfma_f32_16x16x32_bf16 v[28:31], v[132:135], v[180:183], v[28:31]
	v_mfma_f32_16x16x32_bf16 v[24:27], v[140:143], v[180:183], v[24:27]
	v_mfma_f32_16x16x32_bf16 v[12:15], v[132:135], v[188:191], v[12:15]
	v_mfma_f32_16x16x32_bf16 v[8:11], v[140:143], v[188:191], v[8:11]
	v_mfma_f32_16x16x32_bf16 v[52:55], v[144:147], v[160:163], v[52:55]
	v_mfma_f32_16x16x32_bf16 v[48:51], v[152:155], v[160:163], v[48:51]
	v_mfma_f32_16x16x32_bf16 v[36:39], v[144:147], v[168:171], v[36:39]
	v_mfma_f32_16x16x32_bf16 v[32:35], v[152:155], v[168:171], v[32:35]
	v_mfma_f32_16x16x32_bf16 v[20:23], v[144:147], v[176:179], v[20:23]
	v_mfma_f32_16x16x32_bf16 v[16:19], v[152:155], v[176:179], v[16:19]
	v_mfma_f32_16x16x32_bf16 v[4:7], v[144:147], v[184:187], v[4:7]
	v_mfma_f32_16x16x32_bf16 v[0:3], v[152:155], v[184:187], v[0:3]
	v_mfma_f32_16x16x32_bf16 v[52:55], v[148:151], v[164:167], v[52:55]
	v_mfma_f32_16x16x32_bf16 v[48:51], v[156:159], v[164:167], v[48:51]
	v_mfma_f32_16x16x32_bf16 v[36:39], v[148:151], v[172:175], v[36:39]
	v_mfma_f32_16x16x32_bf16 v[32:35], v[156:159], v[172:175], v[32:35]
	v_mfma_f32_16x16x32_bf16 v[20:23], v[148:151], v[180:183], v[20:23]
	v_mfma_f32_16x16x32_bf16 v[16:19], v[156:159], v[180:183], v[16:19]
	v_mfma_f32_16x16x32_bf16 v[4:7], v[148:151], v[188:191], v[4:7]
	v_mfma_f32_16x16x32_bf16 v[0:3], v[156:159], v[188:191], v[0:3]
	s_barrier
	s_add_i32 s76, s76, 2
	s_add_u32 s12, s12, 0x100
	s_addc_u32 s75, s75, 0
	s_cmp_gt_u32 s76, 41
	s_mov_b64 s[48:49], s[6:7]
	s_cbranch_scc0 .LBB0_461
	s_and_b64 vcc, exec, s[24:25]
	s_cbranch_vccz .LBB0_464
	s_barrier

; #define PG8_STAGE(bufoff, gbase, voff) do { _Pragma("unroll") for (int _i = 0; _i < 2; ++_i) \
;         __builtin_amdgcn_global_load_lds((const unsigned*)((const char*)(gbase) + (voff)[_i]), (PG8_LAS unsigned*)(lds + (bufoff) + ldsw + _i * 8192), 16, 0, 0); } while (0)
; #define PG8_LDA(dst, b, h) do { _Pragma("unroll") for (int m = 0; m < 4; ++m) _Pragma("unroll") for (int k = 0; k < 2; ++k) dst[m][k] = *(const PG8_LAS bf16x8*)(lds + PG8_SA(b, h) + aoff + m * 2048 + k * 1024); } while (0)
; #define PG8_LDB(dst, b, h) do { _Pragma("unroll") for (int n = 0; n < 2; ++n) _Pragma("unroll") for (int k = 0; k < 2; ++k) dst[n][k] = *(const PG8_LAS bf16x8*)(lds + PG8_SB(b, h) + boff + n * 2048 + k * 1024); } while (0)
; #define PG8_WAIT_V(n) asm volatile("s_waitcnt vmcnt(" #n ")" ::: "memory")
; template <class Epi, class Sched, bool ALIGN_EPI = false, bool SP2 = false>
; __device__ __forceinline__ void gemm_phase(PG8_LAS unsigned char* lds, const Gemm g, const Sched& S, const Epi& E, int tid_in) {
;     ...
;             const char* a1 = cA + (size_t)(t + 1) * kstep;
;             const char* a2 = last ? nA : cA + (size_t)(t + 2) * kstep; const char* b2 = last ? nB : cB + (size_t)(t + 2) * kstep;
;             const char* a3 = a2 + kstep; const char* b3 = b2 + kstep;
;             if (last && has_next) S.a_ready(nxt);
;             if constexpr (SP2) {
;             PG8_LDB(B0, 0, 0); PG8_LDB(B1, 0, 1); PG8_SCHED; PG8_LDA(At, 0, 0); PG8_STAGE(PG8_SA(1, 1), a1 + hstep, voffA);
;             PG8_WAIT_V(8); PG8_WAIT_L(0); PG8_BAR; PG8_MMA(0, 0, At, B0); PG8_MMA(0, 1, At, B1); PG8_BAR; PG8_SCHED;
;             PG8_LDA(At, 0, 1); PG8_STAGE(PG8_SB(0, 0), b2, voffB); PG8_STAGE(PG8_SB(0, 1), b2 + hstep, voffB); PG8_STAGE(PG8_SA(0, 0), a2, voffA);
;             PG8_WAIT_V(8); PG8_WAIT_L(0); PG8_BAR; PG8_MMA(1, 0, At, B0); PG8_MMA(1, 1, At, B1); PG8_BAR; PG8_SCHED;
;             PG8_LDB(B0, 1, 0); PG8_LDB(B1, 1, 1); PG8_SCHED; PG8_LDA(At, 1, 0); PG8_STAGE(PG8_SA(0, 1), a2 + hstep, voffA);
;             PG8_WAIT_V(8); PG8_WAIT_L(0); PG8_BAR; PG8_MMA(0, 0, At, B0); PG8_MMA(0, 1, At, B1); PG8_BAR; PG8_SCHED;
;             PG8_LDA(At, 1, 1); PG8_STAGE(PG8_SB(1, 0), b3, voffB); PG8_STAGE(PG8_SB(1, 1), b3 + hstep, voffB); PG8_STAGE(PG8_SA(1, 0), a3, voffA);
;             PG8_WAIT_V(8); PG8_WAIT_L(0); PG8_BAR; PG8_MMA(1, 0, At, B0); PG8_MMA(1, 1, At, B1); PG8_BAR; PG8_SCHED;
.LBB0_564:
	s_add_u32 s48, s46, 0xfffc0080
	s_addc_u32 s49, s47, -1
	s_cmp_eq_u32 s52, 12
	s_cselect_b32 s51, s0, s49
	s_cselect_b32 s50, s1, s48
	s_cselect_b32 s49, s7, s45
	s_cselect_b32 s48, s31, s35
	s_add_i32 m0, s59, 0xc000
	ds_read_b128 v[128:131], v180
	global_load_lds_dwordx4 v158, s[46:47]
	s_add_i32 m0, s59, 0xe000
	ds_read_b128 v[132:135], v180 offset:1024
	global_load_lds_dwordx4 v160, s[46:47]
	ds_read_b128 v[136:139], v180 offset:2048
	ds_read_b128 v[140:143], v180 offset:3072
	ds_read_b128 v[166:169], v181
	ds_read_b128 v[170:173], v181 offset:1024
	ds_read_b128 v[174:177], v181 offset:2048
	ds_read_b128 v[184:187], v181 offset:3072
	ds_read_b128 v[188:191], v182
	ds_read_b128 v[192:195], v182 offset:1024
	ds_read_b128 v[196:199], v182 offset:2048
	ds_read_b128 v[200:203], v182 offset:3072
	ds_read_b128 v[204:207], v182 offset:4096
	ds_read_b128 v[208:211], v182 offset:5120
	ds_read_b128 v[212:215], v182 offset:6144
	ds_read_b128 v[216:219], v182 offset:7168
	s_waitcnt vmcnt(8)
	s_waitcnt lgkmcnt(0)
	s_barrier
	v_mfma_f32_16x16x32_bf16 v[68:71], v[128:131], v[188:191], v[68:71]
	v_mfma_f32_16x16x32_bf16 v[56:59], v[136:139], v[188:191], v[56:59]
	v_mfma_f32_16x16x32_bf16 v[52:55], v[128:131], v[196:199], v[52:55]
	v_mfma_f32_16x16x32_bf16 v[48:51], v[136:139], v[196:199], v[48:51]
	v_mfma_f32_16x16x32_bf16 v[44:47], v[128:131], v[204:207], v[44:47]
	v_mfma_f32_16x16x32_bf16 v[40:43], v[136:139], v[204:207], v[40:43]
	v_mfma_f32_16x16x32_bf16 v[36:39], v[128:131], v[212:215], v[36:39]
	v_mfma_f32_16x16x32_bf16 v[32:35], v[136:139], v[212:215], v[32:35]
	v_mfma_f32_16x16x32_bf16 v[68:71], v[132:135], v[192:195], v[68:71]
	v_mfma_f32_16x16x32_bf16 v[56:59], v[140:143], v[192:195], v[56:59]
	v_mfma_f32_16x16x32_bf16 v[52:55], v[132:135], v[200:203], v[52:55]
	v_mfma_f32_16x16x32_bf16 v[48:51], v[140:143], v[200:203], v[48:51]
	v_mfma_f32_16x16x32_bf16 v[44:47], v[132:135], v[208:211], v[44:47]
	v_mfma_f32_16x16x32_bf16 v[40:43], v[140:143], v[208:211], v[40:43]
	v_mfma_f32_16x16x32_bf16 v[36:39], v[132:135], v[216:219], v[36:39]
	v_mfma_f32_16x16x32_bf16 v[32:35], v[140:143], v[216:219], v[32:35]
	v_mfma_f32_16x16x32_bf16 v[124:127], v[166:169], v[188:191], v[124:127]
	v_mfma_f32_16x16x32_bf16 v[120:123], v[174:177], v[188:191], v[120:123]
	v_mfma_f32_16x16x32_bf16 v[116:119], v[166:169], v[196:199], v[116:119]
	v_mfma_f32_16x16x32_bf16 v[112:115], v[174:177], v[196:199], v[112:115]
	v_mfma_f32_16x16x32_bf16 v[108:111], v[166:169], v[204:207], v[108:111]
	v_mfma_f32_16x16x32_bf16 v[104:107], v[174:177], v[204:207], v[104:107]
	v_mfma_f32_16x16x32_bf16 v[100:103], v[166:169], v[212:215], v[100:103]
	v_mfma_f32_16x16x32_bf16 v[96:99], v[174:177], v[212:215], v[96:99]
	v_mfma_f32_16x16x32_bf16 v[124:127], v[170:173], v[192:195], v[124:127]
	v_mfma_f32_16x16x32_bf16 v[120:123], v[184:187], v[192:195], v[120:123]
	v_mfma_f32_16x16x32_bf16 v[116:119], v[170:173], v[200:203], v[116:119]
	v_mfma_f32_16x16x32_bf16 v[112:115], v[184:187], v[200:203], v[112:115]
	v_mfma_f32_16x16x32_bf16 v[108:111], v[170:173], v[208:211], v[108:111]
	v_mfma_f32_16x16x32_bf16 v[104:107], v[184:187], v[208:211], v[104:107]
	v_mfma_f32_16x16x32_bf16 v[100:103], v[170:173], v[216:219], v[100:103]
	v_mfma_f32_16x16x32_bf16 v[96:99], v[184:187], v[216:219], v[96:99]
	s_barrier
	s_add_u32 s98, s48, s14
	s_addc_u32 s99, s49, s15
	s_add_u32 s100, s50, s14
	s_addc_u32 s101, s51, s15
	s_add_i32 s53, s77, s29
	s_mov_b32 m0, s53
	ds_read_b128 v[188:191], v182 offset:16384
	global_load_lds_dwordx4 v146, s[48:49]
	s_add_i32 m0, s53, 0x2000
	s_add_u32 s88, s48, 0x40000
	s_addc_u32 s89, s49, 0
	s_add_i32 s53, s78, s29
	global_load_lds_dwordx4 v150, s[48:49]
	s_mov_b32 m0, s53
	ds_read_b128 v[192:195], v182 offset:17408
	global_load_lds_dwordx4 v146, s[88:89]
	s_add_i32 m0, s53, 0x2000
	ds_read_b128 v[196:199], v182 offset:18432
	global_load_lds_dwordx4 v150, s[88:89]
	s_mov_b32 m0, s59
	ds_read_b128 v[200:203], v182 offset:19456
	global_load_lds_dwordx4 v144, s[50:51]
	s_mov_b32 m0, s60
	ds_read_b128 v[204:207], v182 offset:20480
	global_load_lds_dwordx4 v148, s[50:51]
	ds_read_b128 v[208:211], v182 offset:21504
	ds_read_b128 v[212:215], v182 offset:22528
	ds_read_b128 v[216:219], v182 offset:23552
	s_waitcnt vmcnt(8)
	s_waitcnt lgkmcnt(0)
	s_barrier
	v_mfma_f32_16x16x32_bf16 v[28:31], v[128:131], v[188:191], v[28:31]
	v_mfma_f32_16x16x32_bf16 v[24:27], v[136:139], v[188:191], v[24:27]
	v_mfma_f32_16x16x32_bf16 v[20:23], v[128:131], v[196:199], v[20:23]
	v_mfma_f32_16x16x32_bf16 v[16:19], v[136:139], v[196:199], v[16:19]
	v_mfma_f32_16x16x32_bf16 v[12:15], v[128:131], v[204:207], v[12:15]
	v_mfma_f32_16x16x32_bf16 v[8:11], v[136:139], v[204:207], v[8:11]
	v_mfma_f32_16x16x32_bf16 v[4:7], v[128:131], v[212:215], v[4:7]
	v_mfma_f32_16x16x32_bf16 v[0:3], v[136:139], v[212:215], v[0:3]
	v_mfma_f32_16x16x32_bf16 v[28:31], v[132:135], v[192:195], v[28:31]
	v_mfma_f32_16x16x32_bf16 v[24:27], v[140:143], v[192:195], v[24:27]
	v_mfma_f32_16x16x32_bf16 v[20:23], v[132:135], v[200:203], v[20:23]
	v_mfma_f32_16x16x32_bf16 v[16:19], v[140:143], v[200:203], v[16:19]
	v_mfma_f32_16x16x32_bf16 v[12:15], v[132:135], v[208:211], v[12:15]
	v_mfma_f32_16x16x32_bf16 v[8:11], v[140:143], v[208:211], v[8:11]
	v_mfma_f32_16x16x32_bf16 v[4:7], v[132:135], v[216:219], v[4:7]
	v_mfma_f32_16x16x32_bf16 v[0:3], v[140:143], v[216:219], v[0:3]
	v_mfma_f32_16x16x32_bf16 v[92:95], v[166:169], v[188:191], v[92:95]
	v_mfma_f32_16x16x32_bf16 v[88:91], v[174:177], v[188:191], v[88:91]
	v_mfma_f32_16x16x32_bf16 v[84:87], v[166:169], v[196:199], v[84:87]
	v_mfma_f32_16x16x32_bf16 v[80:83], v[174:177], v[196:199], v[80:83]
	v_mfma_f32_16x16x32_bf16 v[76:79], v[166:169], v[204:207], v[76:79]
	v_mfma_f32_16x16x32_bf16 v[72:75], v[174:177], v[204:207], v[72:75]
	v_mfma_f32_16x16x32_bf16 v[64:67], v[166:169], v[212:215], v[64:67]
	v_mfma_f32_16x16x32_bf16 v[60:63], v[174:177], v[212:215], v[60:63]
	v_mfma_f32_16x16x32_bf16 v[92:95], v[170:173], v[192:195], v[92:95]
	v_mfma_f32_16x16x32_bf16 v[88:91], v[184:187], v[192:195], v[88:91]
	v_mfma_f32_16x16x32_bf16 v[84:87], v[170:173], v[200:203], v[84:87]
	v_mfma_f32_16x16x32_bf16 v[80:83], v[184:187], v[200:203], v[80:83]
	v_mfma_f32_16x16x32_bf16 v[76:79], v[170:173], v[208:211], v[76:79]
	v_mfma_f32_16x16x32_bf16 v[72:75], v[184:187], v[208:211], v[72:75]
	v_mfma_f32_16x16x32_bf16 v[64:67], v[170:173], v[216:219], v[64:67]
	v_mfma_f32_16x16x32_bf16 v[60:63], v[184:187], v[216:219], v[60:63]
	s_barrier
; #define PG8_STAGE(bufoff, gbase, voff) do { _Pragma("unroll") for (int _i = 0; _i < 2; ++_i) \
;         __builtin_amdgcn_global_load_lds((const unsigned*)((const char*)(gbase) + (voff)[_i]), (PG8_LAS unsigned*)(lds + (bufoff) + ldsw + _i * 8192), 16, 0, 0); } while (0)
; #define PG8_LDA(dst, b, h) do { _Pragma("unroll") for (int m = 0; m < 4; ++m) _Pragma("unroll") for (int k = 0; k < 2; ++k) dst[m][k] = *(const PG8_LAS bf16x8*)(lds + PG8_SA(b, h) + aoff + m * 2048 + k * 1024); } while (0)
; #define PG8_WAIT_V(n) asm volatile("s_waitcnt vmcnt(" #n ")" ::: "memory")
; #define PG8_BAR __builtin_amdgcn_s_barrier()
;     __device__ __forceinline__ void operator()(const f32x4 (&acc)[2][2][4][2], const Unit& u, int wr, int wc, int fr, int fq) const {
;     ...
;         if (pn == 19) {
; template <class Epi, class Sched, bool ALIGN_EPI = false, bool SP2 = false>
; __device__ __forceinline__ void gemm_phase(PG8_LAS unsigned char* lds, const Gemm g, const Sched& S, const Epi& E, int tid_in) {
;     ...
;             const char* a1 = cA + (size_t)(t + 1) * kstep;
;             const char* a2 = last ? nA : cA + (size_t)(t + 2) * kstep; const char* b2 = last ? nB : cB + (size_t)(t + 2) * kstep;
;             const char* a3 = a2 + kstep; const char* b3 = b2 + kstep;
;             if (last && has_next) S.a_ready(nxt);
;             if constexpr (SP2) {
;             PG8_LDB(B0, 0, 0); PG8_LDB(B1, 0, 1); PG8_SCHED; PG8_LDA(At, 0, 0); PG8_STAGE(PG8_SA(1, 1), a1 + hstep, voffA);
;             PG8_WAIT_V(8); PG8_WAIT_L(0); PG8_BAR; PG8_MMA(0, 0, At, B0); PG8_MMA(0, 1, At, B1); PG8_BAR; PG8_SCHED;
;             PG8_LDA(At, 0, 1); PG8_STAGE(PG8_SB(0, 0), b2, voffB); PG8_STAGE(PG8_SB(0, 1), b2 + hstep, voffB); PG8_STAGE(PG8_SA(0, 0), a2, voffA);
;             PG8_WAIT_V(8); PG8_WAIT_L(0); PG8_BAR; PG8_MMA(1, 0, At, B0); PG8_MMA(1, 1, At, B1); PG8_BAR; PG8_SCHED;
;             PG8_LDB(B0, 1, 0); PG8_LDB(B1, 1, 1); PG8_SCHED; PG8_LDA(At, 1, 0); PG8_STAGE(PG8_SA(0, 1), a2 + hstep, voffA);
;             PG8_WAIT_V(8); PG8_WAIT_L(0); PG8_BAR; PG8_MMA(0, 0, At, B0); PG8_MMA(0, 1, At, B1); PG8_BAR; PG8_SCHED;
;             PG8_LDA(At, 1, 1); PG8_STAGE(PG8_SB(1, 0), b3, voffB); PG8_STAGE(PG8_SB(1, 1), b3 + hstep, voffB); PG8_STAGE(PG8_SA(1, 0), a3, voffA);
;             PG8_WAIT_V(8); PG8_WAIT_L(0); PG8_BAR; PG8_MMA(1, 0, At, B0); PG8_MMA(1, 1, At, B1); PG8_BAR; PG8_SCHED;
	s_add_i32 s53, 0, 0x18000
	s_add_i32 s88, 0, 0x1c000
	s_add_u32 s50, s50, 0x40000
	s_addc_u32 s51, s51, 0
	s_mov_b32 m0, s61
	s_nop 0
	global_load_lds_dwordx4 v144, s[50:51]
	s_mov_b32 m0, s62
	s_nop 0
	global_load_lds_dwordx4 v148, s[50:51]
	v_add_u32_e32 v140, s53, v179
	v_add_u32_e32 v184, s88, v179
	ds_read_b128 v[128:131], v140
	ds_read_b128 v[132:135], v140 offset:1024
	ds_read_b128 v[136:139], v140 offset:2048
	ds_read_b128 v[140:143], v140 offset:3072
	ds_read_b128 v[166:169], v184
	ds_read_b128 v[170:173], v184 offset:1024
	ds_read_b128 v[174:177], v184 offset:2048
	ds_read_b128 v[184:187], v184 offset:3072
	ds_read_b128 v[188:191], v182 offset:32768
	ds_read_b128 v[192:195], v182 offset:33792
	ds_read_b128 v[196:199], v182 offset:34816
	ds_read_b128 v[200:203], v182 offset:35840
	ds_read_b128 v[204:207], v182 offset:36864
	ds_read_b128 v[208:211], v182 offset:37888
	ds_read_b128 v[212:215], v182 offset:38912
	ds_read_b128 v[216:219], v182 offset:39936
	s_waitcnt vmcnt(8)
	s_waitcnt lgkmcnt(0)
	s_barrier
	v_mfma_f32_16x16x32_bf16 v[68:71], v[128:131], v[188:191], v[68:71]
	v_mfma_f32_16x16x32_bf16 v[56:59], v[136:139], v[188:191], v[56:59]
	v_mfma_f32_16x16x32_bf16 v[52:55], v[128:131], v[196:199], v[52:55]
	v_mfma_f32_16x16x32_bf16 v[48:51], v[136:139], v[196:199], v[48:51]
	v_mfma_f32_16x16x32_bf16 v[44:47], v[128:131], v[204:207], v[44:47]
	v_mfma_f32_16x16x32_bf16 v[40:43], v[136:139], v[204:207], v[40:43]
	v_mfma_f32_16x16x32_bf16 v[36:39], v[128:131], v[212:215], v[36:39]
	v_mfma_f32_16x16x32_bf16 v[32:35], v[136:139], v[212:215], v[32:35]
	v_mfma_f32_16x16x32_bf16 v[68:71], v[132:135], v[192:195], v[68:71]
	v_mfma_f32_16x16x32_bf16 v[56:59], v[140:143], v[192:195], v[56:59]
	v_mfma_f32_16x16x32_bf16 v[52:55], v[132:135], v[200:203], v[52:55]
	v_mfma_f32_16x16x32_bf16 v[48:51], v[140:143], v[200:203], v[48:51]
	v_mfma_f32_16x16x32_bf16 v[44:47], v[132:135], v[208:211], v[44:47]
	v_mfma_f32_16x16x32_bf16 v[40:43], v[140:143], v[208:211], v[40:43]
	v_mfma_f32_16x16x32_bf16 v[36:39], v[132:135], v[216:219], v[36:39]
	v_mfma_f32_16x16x32_bf16 v[32:35], v[140:143], v[216:219], v[32:35]
	v_mfma_f32_16x16x32_bf16 v[124:127], v[166:169], v[188:191], v[124:127]
	v_mfma_f32_16x16x32_bf16 v[120:123], v[174:177], v[188:191], v[120:123]
	v_mfma_f32_16x16x32_bf16 v[116:119], v[166:169], v[196:199], v[116:119]
	v_mfma_f32_16x16x32_bf16 v[112:115], v[174:177], v[196:199], v[112:115]
	v_mfma_f32_16x16x32_bf16 v[108:111], v[166:169], v[204:207], v[108:111]
	v_mfma_f32_16x16x32_bf16 v[104:107], v[174:177], v[204:207], v[104:107]
	v_mfma_f32_16x16x32_bf16 v[100:103], v[166:169], v[212:215], v[100:103]
	v_mfma_f32_16x16x32_bf16 v[96:99], v[174:177], v[212:215], v[96:99]
	v_mfma_f32_16x16x32_bf16 v[124:127], v[170:173], v[192:195], v[124:127]
	v_mfma_f32_16x16x32_bf16 v[120:123], v[184:187], v[192:195], v[120:123]
	v_mfma_f32_16x16x32_bf16 v[116:119], v[170:173], v[200:203], v[116:119]
	v_mfma_f32_16x16x32_bf16 v[112:115], v[184:187], v[200:203], v[112:115]
	v_mfma_f32_16x16x32_bf16 v[108:111], v[170:173], v[208:211], v[108:111]
	v_mfma_f32_16x16x32_bf16 v[104:107], v[184:187], v[208:211], v[104:107]
	v_mfma_f32_16x16x32_bf16 v[100:103], v[170:173], v[216:219], v[100:103]
	v_mfma_f32_16x16x32_bf16 v[96:99], v[184:187], v[216:219], v[96:99]
	s_barrier
	s_add_i32 s50, s53, s29
	s_mov_b32 m0, s50
	ds_read_b128 v[188:191], v182 offset:49152
	global_load_lds_dwordx4 v146, s[98:99]
	s_add_i32 m0, s50, 0x2000
	s_add_u32 s48, s48, 0x40080
	s_addc_u32 s49, s49, 0
	s_add_i32 s50, s88, s29
	global_load_lds_dwordx4 v150, s[98:99]
	s_mov_b32 m0, s50
	ds_read_b128 v[192:195], v182 offset:50176
	global_load_lds_dwordx4 v146, s[48:49]
	s_add_i32 m0, s50, 0x2000
	ds_read_b128 v[196:199], v182 offset:51200
	global_load_lds_dwordx4 v150, s[48:49]
	s_mov_b32 m0, s63
	ds_read_b128 v[200:203], v182 offset:52224
	global_load_lds_dwordx4 v144, s[100:101]
	s_mov_b32 m0, s64
	ds_read_b128 v[204:207], v182 offset:53248
	global_load_lds_dwordx4 v148, s[100:101]
	ds_read_b128 v[208:211], v182 offset:54272
	ds_read_b128 v[212:215], v182 offset:55296
	ds_read_b128 v[216:219], v182 offset:56320
	s_waitcnt vmcnt(8)
	s_waitcnt lgkmcnt(0)
	s_barrier
	v_mfma_f32_16x16x32_bf16 v[28:31], v[128:131], v[188:191], v[28:31]
	v_mfma_f32_16x16x32_bf16 v[24:27], v[136:139], v[188:191], v[24:27]
	v_mfma_f32_16x16x32_bf16 v[20:23], v[128:131], v[196:199], v[20:23]
	v_mfma_f32_16x16x32_bf16 v[16:19], v[136:139], v[196:199], v[16:19]
	v_mfma_f32_16x16x32_bf16 v[12:15], v[128:131], v[204:207], v[12:15]
	v_mfma_f32_16x16x32_bf16 v[8:11], v[136:139], v[204:207], v[8:11]
	v_mfma_f32_16x16x32_bf16 v[4:7], v[128:131], v[212:215], v[4:7]
	v_mfma_f32_16x16x32_bf16 v[0:3], v[136:139], v[212:215], v[0:3]
	v_mfma_f32_16x16x32_bf16 v[28:31], v[132:135], v[192:195], v[28:31]
	v_mfma_f32_16x16x32_bf16 v[24:27], v[140:143], v[192:195], v[24:27]
	v_mfma_f32_16x16x32_bf16 v[20:23], v[132:135], v[200:203], v[20:23]
	v_mfma_f32_16x16x32_bf16 v[16:19], v[140:143], v[200:203], v[16:19]
	v_mfma_f32_16x16x32_bf16 v[12:15], v[132:135], v[208:211], v[12:15]
	v_mfma_f32_16x16x32_bf16 v[8:11], v[140:143], v[208:211], v[8:11]
	v_mfma_f32_16x16x32_bf16 v[4:7], v[132:135], v[216:219], v[4:7]
	v_mfma_f32_16x16x32_bf16 v[0:3], v[140:143], v[216:219], v[0:3]
	v_mfma_f32_16x16x32_bf16 v[92:95], v[166:169], v[188:191], v[92:95]
	v_mfma_f32_16x16x32_bf16 v[88:91], v[174:177], v[188:191], v[88:91]
	v_mfma_f32_16x16x32_bf16 v[84:87], v[166:169], v[196:199], v[84:87]
	v_mfma_f32_16x16x32_bf16 v[80:83], v[174:177], v[196:199], v[80:83]
	v_mfma_f32_16x16x32_bf16 v[76:79], v[166:169], v[204:207], v[76:79]
	v_mfma_f32_16x16x32_bf16 v[72:75], v[174:177], v[204:207], v[72:75]
	v_mfma_f32_16x16x32_bf16 v[64:67], v[166:169], v[212:215], v[64:67]
	v_mfma_f32_16x16x32_bf16 v[60:63], v[174:177], v[212:215], v[60:63]
	v_mfma_f32_16x16x32_bf16 v[92:95], v[170:173], v[192:195], v[92:95]
	v_mfma_f32_16x16x32_bf16 v[88:91], v[184:187], v[192:195], v[88:91]
	v_mfma_f32_16x16x32_bf16 v[84:87], v[170:173], v[200:203], v[84:87]
	v_mfma_f32_16x16x32_bf16 v[80:83], v[184:187], v[200:203], v[80:83]
	v_mfma_f32_16x16x32_bf16 v[76:79], v[170:173], v[208:211], v[76:79]
	v_mfma_f32_16x16x32_bf16 v[72:75], v[184:187], v[208:211], v[72:75]
	v_mfma_f32_16x16x32_bf16 v[64:67], v[170:173], v[216:219], v[64:67]
	v_mfma_f32_16x16x32_bf16 v[60:63], v[184:187], v[216:219], v[60:63]
	s_barrier
	s_add_i32 s52, s52, 2
	s_add_u32 s46, s46, 0x100
	s_addc_u32 s47, s47, 0
	s_add_u32 s35, s35, 0x100
	s_addc_u32 s45, s45, 0
	s_cmp_gt_u32 s52, 13
	s_cbranch_scc0 .LBB0_564
	s_and_b64 vcc, exec, s[16:17]
	s_cbranch_vccnz .LBB0_568
	v_lshl_add_u32 v166, s44, 8, v178
	s_cmp_lg_u32 s6, 19
	s_mov_b64 s[44:45], -1
	s_cbranch_scc1 .LBB0_569

; #define PG8_STAGE(bufoff, gbase, voff) do { _Pragma("unroll") for (int _i = 0; _i < 2; ++_i) \
;         __builtin_amdgcn_global_load_lds((const unsigned*)((const char*)(gbase) + (voff)[_i]), (PG8_LAS unsigned*)(lds + (bufoff) + ldsw + _i * 8192), 16, 0, 0); } while (0)
; #define PG8_LDA(dst, b, h) do { _Pragma("unroll") for (int m = 0; m < 4; ++m) _Pragma("unroll") for (int k = 0; k < 2; ++k) dst[m][k] = *(const PG8_LAS bf16x8*)(lds + PG8_SA(b, h) + aoff + m * 2048 + k * 1024); } while (0)
; #define PG8_LDB(dst, b, h) do { _Pragma("unroll") for (int n = 0; n < 2; ++n) _Pragma("unroll") for (int k = 0; k < 2; ++k) dst[n][k] = *(const PG8_LAS bf16x8*)(lds + PG8_SB(b, h) + boff + n * 2048 + k * 1024); } while (0)
; #define PG8_WAIT_V(n) asm volatile("s_waitcnt vmcnt(" #n ")" ::: "memory")
; #define PG8_WAIT_L(n) asm volatile("s_waitcnt lgkmcnt(" #n ")" ::: "memory")
; #define PG8_BAR __builtin_amdgcn_s_barrier()
; #define PG8_SCHED __builtin_amdgcn_sched_barrier(0)
; template <class Epi, class Sched, bool ALIGN_EPI = false, bool SP2 = false>
; __device__ __forceinline__ void gemm_phase(PG8_LAS unsigned char* lds, const Gemm g, const Sched& S, const Epi& E, int tid_in) {
;     ...
;             const char* a1 = cA + (size_t)(t + 1) * kstep;
;             const char* a2 = last ? nA : cA + (size_t)(t + 2) * kstep; const char* b2 = last ? nB : cB + (size_t)(t + 2) * kstep;
;             const char* a3 = a2 + kstep; const char* b3 = b2 + kstep;
;             if (last && has_next) S.a_ready(nxt);
;             if constexpr (SP2) {
;             PG8_LDB(B0, 0, 0); PG8_LDB(B1, 0, 1); PG8_SCHED; PG8_LDA(At, 0, 0); PG8_STAGE(PG8_SA(1, 1), a1 + hstep, voffA);
;             PG8_WAIT_V(8); PG8_WAIT_L(0); PG8_BAR; PG8_MMA(0, 0, At, B0); PG8_MMA(0, 1, At, B1); PG8_BAR; PG8_SCHED;
;             PG8_LDA(At, 0, 1); PG8_STAGE(PG8_SB(0, 0), b2, voffB); PG8_STAGE(PG8_SB(0, 1), b2 + hstep, voffB); PG8_STAGE(PG8_SA(0, 0), a2, voffA);
;             PG8_WAIT_V(8); PG8_WAIT_L(0); PG8_BAR; PG8_MMA(1, 0, At, B0); PG8_MMA(1, 1, At, B1); PG8_BAR; PG8_SCHED;
;             PG8_LDB(B0, 1, 0); PG8_LDB(B1, 1, 1); PG8_SCHED; PG8_LDA(At, 1, 0); PG8_STAGE(PG8_SA(0, 1), a2 + hstep, voffA);
;             PG8_WAIT_V(8); PG8_WAIT_L(0); PG8_BAR; PG8_MMA(0, 0, At, B0); PG8_MMA(0, 1, At, B1); PG8_BAR; PG8_SCHED;
.LBB0_1062:
	s_add_u32 s0, s44, s46
	s_addc_u32 s1, s45, s47
	s_add_u32 s0, s0, 0x100
	s_addc_u32 s1, s1, 0
	s_add_u32 s48, s78, s46
	s_addc_u32 s49, s79, s47
	s_add_i32 s81, 0, 0x10000
	v_add_u32_e32 v1, s81, v214
	ds_read_b128 v[132:135], v1
	ds_read_b128 v[136:139], v1 offset:1024
	ds_read_b128 v[140:143], v1 offset:2048
	ds_read_b128 v[144:147], v1 offset:3072
	v_add_u32_e32 v1, s74, v214
	ds_read_b128 v[148:151], v1
	ds_read_b128 v[152:155], v1 offset:1024
	ds_read_b128 v[156:159], v1 offset:2048
	ds_read_b128 v[160:163], v1 offset:3072
	s_cmpk_eq_i32 s46, 0x700
	s_cselect_b32 s51, s35, s1
	s_cselect_b32 s50, s67, s0
	s_cselect_b32 s49, s75, s49
	s_cselect_b32 s48, s76, s48
	v_lshl_add_u64 v[2:3], v[208:209], 0, s[46:47]
	s_add_i32 m0, s58, 0xc000
	ds_read_b128 v[164:167], v216
	ds_read_b128 v[168:171], v216 offset:1024
	ds_read_b128 v[172:175], v216 offset:2048
	ds_read_b128 v[176:179], v216 offset:3072
	ds_read_b128 v[180:183], v216 offset:4096
	ds_read_b128 v[184:187], v216 offset:5120
	ds_read_b128 v[218:221], v216 offset:6144
	ds_read_b128 v[222:225], v216 offset:7168
	global_load_lds_dwordx4 v[2:3], off
	v_lshl_add_u64 v[2:3], v[210:211], 0, s[46:47]
	s_add_i32 m0, s58, 0xe000
	s_nop 0
	global_load_lds_dwordx4 v[2:3], off
	s_waitcnt vmcnt(8)
	s_waitcnt lgkmcnt(0)
	s_barrier
	v_mfma_f32_16x16x32_bf16 v[128:131], v[132:135], v[164:167], v[128:131]
	v_mfma_f32_16x16x32_bf16 v[124:127], v[140:143], v[164:167], v[124:127]
	v_mfma_f32_16x16x32_bf16 v[112:115], v[132:135], v[172:175], v[112:115]
	v_mfma_f32_16x16x32_bf16 v[108:111], v[140:143], v[172:175], v[108:111]
	v_mfma_f32_16x16x32_bf16 v[96:99], v[132:135], v[180:183], v[96:99]
	v_mfma_f32_16x16x32_bf16 v[92:95], v[140:143], v[180:183], v[92:95]
	v_mfma_f32_16x16x32_bf16 v[80:83], v[132:135], v[218:221], v[80:83]
	v_mfma_f32_16x16x32_bf16 v[76:79], v[140:143], v[218:221], v[76:79]
	v_mfma_f32_16x16x32_bf16 v[128:131], v[136:139], v[168:171], v[128:131]
	v_mfma_f32_16x16x32_bf16 v[124:127], v[144:147], v[168:171], v[124:127]
	v_mfma_f32_16x16x32_bf16 v[112:115], v[136:139], v[176:179], v[112:115]
	v_mfma_f32_16x16x32_bf16 v[108:111], v[144:147], v[176:179], v[108:111]
	v_mfma_f32_16x16x32_bf16 v[96:99], v[136:139], v[184:187], v[96:99]
	v_mfma_f32_16x16x32_bf16 v[92:95], v[144:147], v[184:187], v[92:95]
	v_mfma_f32_16x16x32_bf16 v[80:83], v[136:139], v[222:225], v[80:83]
	v_mfma_f32_16x16x32_bf16 v[76:79], v[144:147], v[222:225], v[76:79]
	v_mfma_f32_16x16x32_bf16 v[120:123], v[148:151], v[164:167], v[120:123]
	v_mfma_f32_16x16x32_bf16 v[116:119], v[156:159], v[164:167], v[116:119]
	v_mfma_f32_16x16x32_bf16 v[104:107], v[148:151], v[172:175], v[104:107]
	v_mfma_f32_16x16x32_bf16 v[100:103], v[156:159], v[172:175], v[100:103]
	v_mfma_f32_16x16x32_bf16 v[88:91], v[148:151], v[180:183], v[88:91]
	v_mfma_f32_16x16x32_bf16 v[84:87], v[156:159], v[180:183], v[84:87]
	v_mfma_f32_16x16x32_bf16 v[72:75], v[148:151], v[218:221], v[72:75]
	v_mfma_f32_16x16x32_bf16 v[68:71], v[156:159], v[218:221], v[68:71]
	v_mfma_f32_16x16x32_bf16 v[120:123], v[152:155], v[168:171], v[120:123]
	v_mfma_f32_16x16x32_bf16 v[116:119], v[160:163], v[168:171], v[116:119]
	v_mfma_f32_16x16x32_bf16 v[104:107], v[152:155], v[176:179], v[104:107]
	v_mfma_f32_16x16x32_bf16 v[100:103], v[160:163], v[176:179], v[100:103]
	v_mfma_f32_16x16x32_bf16 v[88:91], v[152:155], v[184:187], v[88:91]
	v_mfma_f32_16x16x32_bf16 v[84:87], v[160:163], v[184:187], v[84:87]
	v_mfma_f32_16x16x32_bf16 v[72:75], v[152:155], v[222:225], v[72:75]
	v_mfma_f32_16x16x32_bf16 v[68:71], v[160:163], v[222:225], v[68:71]
	s_barrier
	s_add_i32 s0, s81, s57
	v_lshl_add_u64 v[226:227], s[48:49], 0, v[190:191]
	s_mov_b32 m0, s0
	ds_read_b128 v[164:167], v216 offset:16384
	ds_read_b128 v[168:171], v216 offset:17408
	ds_read_b128 v[172:175], v216 offset:18432
	ds_read_b128 v[176:179], v216 offset:19456
	ds_read_b128 v[180:183], v216 offset:20480
	ds_read_b128 v[184:187], v216 offset:21504
	ds_read_b128 v[218:221], v216 offset:22528
	ds_read_b128 v[222:225], v216 offset:23552
	global_load_lds_dwordx4 v[226:227], off
	s_add_i32 m0, s0, 0x2000
	s_add_u32 s0, s48, 0x40000
	v_lshl_add_u64 v[228:229], s[48:49], 0, v[194:195]
	s_addc_u32 s1, s49, 0
	s_add_i32 s81, s74, s57
	global_load_lds_dwordx4 v[228:229], off
	v_lshl_add_u64 v[2:3], s[0:1], 0, v[190:191]
	s_mov_b32 m0, s81
	v_lshl_add_u64 v[232:233], s[50:51], 0, v[188:189]
	global_load_lds_dwordx4 v[2:3], off
	v_lshl_add_u64 v[2:3], s[0:1], 0, v[194:195]
	s_add_i32 m0, s81, 0x2000
	v_lshl_add_u64 v[234:235], s[50:51], 0, v[192:193]
	global_load_lds_dwordx4 v[2:3], off
	s_mov_b32 m0, s58
	s_nop 0
	global_load_lds_dwordx4 v[232:233], off
	s_mov_b32 m0, s59
	s_nop 0
	global_load_lds_dwordx4 v[234:235], off
	s_waitcnt vmcnt(8)
	s_waitcnt lgkmcnt(0)
	s_barrier
; #define PG8_STAGE(bufoff, gbase, voff) do { _Pragma("unroll") for (int _i = 0; _i < 2; ++_i) \
;         __builtin_amdgcn_global_load_lds((const unsigned*)((const char*)(gbase) + (voff)[_i]), (PG8_LAS unsigned*)(lds + (bufoff) + ldsw + _i * 8192), 16, 0, 0); } while (0)
; #define PG8_LDA(dst, b, h) do { _Pragma("unroll") for (int m = 0; m < 4; ++m) _Pragma("unroll") for (int k = 0; k < 2; ++k) dst[m][k] = *(const PG8_LAS bf16x8*)(lds + PG8_SA(b, h) + aoff + m * 2048 + k * 1024); } while (0)
; #define PG8_LDB(dst, b, h) do { _Pragma("unroll") for (int n = 0; n < 2; ++n) _Pragma("unroll") for (int k = 0; k < 2; ++k) dst[n][k] = *(const PG8_LAS bf16x8*)(lds + PG8_SB(b, h) + boff + n * 2048 + k * 1024); } while (0)
; #define PG8_MMA(ai, bj, At, Bt) do { __builtin_amdgcn_s_setprio(1); _Pragma("unroll") for (int m = 0; m < 4; ++m) _Pragma("unroll") for (int n = 0; n < 2; ++n) _Pragma("unroll") for (int k = 0; k < 2; ++k) \
;         acc[ai][bj][m][n] = __builtin_amdgcn_mfma_f32_16x16x32_bf16(Bt[n][k], At[m][k], acc[ai][bj][m][n], 0, 0, 0); __builtin_amdgcn_s_setprio(0); } while (0)
; #define PG8_WAIT_V(n) asm volatile("s_waitcnt vmcnt(" #n ")" ::: "memory")
; #define PG8_WAIT_L(n) asm volatile("s_waitcnt lgkmcnt(" #n ")" ::: "memory")
; #define PG8_BAR __builtin_amdgcn_s_barrier()
; #define PG8_SCHED __builtin_amdgcn_sched_barrier(0)
; template <class Epi, class Sched, bool ALIGN_EPI = false, bool SP2 = false>
; __device__ __forceinline__ void gemm_phase(PG8_LAS unsigned char* lds, const Gemm g, const Sched& S, const Epi& E, int tid_in) {
;     ...
;             PG8_WAIT_V(8); PG8_WAIT_L(0); PG8_BAR; PG8_MMA(1, 0, At, B0); PG8_MMA(1, 1, At, B1); PG8_BAR; PG8_SCHED;
;             PG8_LDB(B0, 1, 0); PG8_LDB(B1, 1, 1); PG8_SCHED; PG8_LDA(At, 1, 0); PG8_STAGE(PG8_SA(0, 1), a2 + hstep, voffA);
;             PG8_WAIT_V(8); PG8_WAIT_L(0); PG8_BAR; PG8_MMA(0, 0, At, B0); PG8_MMA(0, 1, At, B1); PG8_BAR; PG8_SCHED;
;             PG8_LDA(At, 1, 1); PG8_STAGE(PG8_SB(1, 0), b3, voffB); PG8_STAGE(PG8_SB(1, 1), b3 + hstep, voffB); PG8_STAGE(PG8_SA(1, 0), a3, voffA);
;             PG8_WAIT_V(8); PG8_WAIT_L(0); PG8_BAR; PG8_MMA(1, 0, At, B0); PG8_MMA(1, 1, At, B1); PG8_BAR; PG8_SCHED;
	v_mfma_f32_16x16x32_bf16 v[64:67], v[132:135], v[164:167], v[64:67]
	v_mfma_f32_16x16x32_bf16 v[60:63], v[140:143], v[164:167], v[60:63]
	v_mfma_f32_16x16x32_bf16 v[48:51], v[132:135], v[172:175], v[48:51]
	v_mfma_f32_16x16x32_bf16 v[44:47], v[140:143], v[172:175], v[44:47]
	v_mfma_f32_16x16x32_bf16 v[32:35], v[132:135], v[180:183], v[32:35]
	v_mfma_f32_16x16x32_bf16 v[28:31], v[140:143], v[180:183], v[28:31]
	v_mfma_f32_16x16x32_bf16 v[16:19], v[132:135], v[218:221], v[16:19]
	v_mfma_f32_16x16x32_bf16 v[12:15], v[140:143], v[218:221], v[12:15]
	v_mfma_f32_16x16x32_bf16 v[64:67], v[136:139], v[168:171], v[64:67]
	v_mfma_f32_16x16x32_bf16 v[60:63], v[144:147], v[168:171], v[60:63]
	v_mfma_f32_16x16x32_bf16 v[48:51], v[136:139], v[176:179], v[48:51]
	v_mfma_f32_16x16x32_bf16 v[44:47], v[144:147], v[176:179], v[44:47]
	v_mfma_f32_16x16x32_bf16 v[32:35], v[136:139], v[184:187], v[32:35]
	v_mfma_f32_16x16x32_bf16 v[28:31], v[144:147], v[184:187], v[28:31]
	v_mfma_f32_16x16x32_bf16 v[16:19], v[136:139], v[222:225], v[16:19]
	v_mfma_f32_16x16x32_bf16 v[12:15], v[144:147], v[222:225], v[12:15]
	v_mfma_f32_16x16x32_bf16 v[56:59], v[148:151], v[164:167], v[56:59]
	v_mfma_f32_16x16x32_bf16 v[52:55], v[156:159], v[164:167], v[52:55]
	v_mfma_f32_16x16x32_bf16 v[40:43], v[148:151], v[172:175], v[40:43]
	v_mfma_f32_16x16x32_bf16 v[36:39], v[156:159], v[172:175], v[36:39]
	v_mfma_f32_16x16x32_bf16 v[24:27], v[148:151], v[180:183], v[24:27]
	v_mfma_f32_16x16x32_bf16 v[20:23], v[156:159], v[180:183], v[20:23]
	v_mfma_f32_16x16x32_bf16 v[8:11], v[148:151], v[218:221], v[8:11]
	v_mfma_f32_16x16x32_bf16 v[2:5], v[156:159], v[218:221], v[4:7]
	v_mfma_f32_16x16x32_bf16 v[56:59], v[152:155], v[168:171], v[56:59]
	v_mfma_f32_16x16x32_bf16 v[52:55], v[160:163], v[168:171], v[52:55]
	v_mfma_f32_16x16x32_bf16 v[40:43], v[152:155], v[176:179], v[40:43]
	v_mfma_f32_16x16x32_bf16 v[36:39], v[160:163], v[176:179], v[36:39]
	v_mfma_f32_16x16x32_bf16 v[24:27], v[152:155], v[184:187], v[24:27]
	v_mfma_f32_16x16x32_bf16 v[20:23], v[160:163], v[184:187], v[20:23]
	v_mfma_f32_16x16x32_bf16 v[8:11], v[152:155], v[222:225], v[8:11]
	v_mfma_f32_16x16x32_bf16 v[2:5], v[160:163], v[222:225], v[2:5]
	s_barrier
	s_add_i32 s81, 0, 0x18000
	v_add_u32_e32 v1, s81, v214
	s_add_i32 s82, 0, 0x1c000
	ds_read_b128 v[132:135], v1
	ds_read_b128 v[136:139], v1 offset:1024
	ds_read_b128 v[140:143], v1 offset:2048
	ds_read_b128 v[144:147], v1 offset:3072
	v_add_u32_e32 v1, s82, v214
	ds_read_b128 v[148:151], v1
	ds_read_b128 v[152:155], v1 offset:1024
	ds_read_b128 v[156:159], v1 offset:2048
	ds_read_b128 v[160:163], v1 offset:3072
	s_add_u32 s0, s50, 0x40000
	s_addc_u32 s1, s51, 0
	s_mov_b32 m0, s60
	v_lshl_add_u64 v[6:7], s[0:1], 0, v[188:189]
	ds_read_b128 v[164:167], v216 offset:32768
	ds_read_b128 v[168:171], v216 offset:33792
	ds_read_b128 v[172:175], v216 offset:34816
	ds_read_b128 v[176:179], v216 offset:35840
	ds_read_b128 v[180:183], v216 offset:36864
	ds_read_b128 v[184:187], v216 offset:37888
	ds_read_b128 v[218:221], v216 offset:38912
	ds_read_b128 v[222:225], v216 offset:39936
	global_load_lds_dwordx4 v[6:7], off
	v_lshl_add_u64 v[6:7], s[0:1], 0, v[192:193]
	s_mov_b32 m0, s61
	s_nop 0
	global_load_lds_dwordx4 v[6:7], off
	s_waitcnt vmcnt(8)
	s_waitcnt lgkmcnt(0)
	s_barrier
	v_mfma_f32_16x16x32_bf16 v[128:131], v[132:135], v[164:167], v[128:131]
	v_mfma_f32_16x16x32_bf16 v[124:127], v[140:143], v[164:167], v[124:127]
	v_mfma_f32_16x16x32_bf16 v[112:115], v[132:135], v[172:175], v[112:115]
	v_mfma_f32_16x16x32_bf16 v[108:111], v[140:143], v[172:175], v[108:111]
	v_mfma_f32_16x16x32_bf16 v[96:99], v[132:135], v[180:183], v[96:99]
	v_mfma_f32_16x16x32_bf16 v[92:95], v[140:143], v[180:183], v[92:95]
	v_mfma_f32_16x16x32_bf16 v[80:83], v[132:135], v[218:221], v[80:83]
	v_mfma_f32_16x16x32_bf16 v[76:79], v[140:143], v[218:221], v[76:79]
	v_mfma_f32_16x16x32_bf16 v[128:131], v[136:139], v[168:171], v[128:131]
	v_mfma_f32_16x16x32_bf16 v[124:127], v[144:147], v[168:171], v[124:127]
	v_mfma_f32_16x16x32_bf16 v[112:115], v[136:139], v[176:179], v[112:115]
	v_mfma_f32_16x16x32_bf16 v[108:111], v[144:147], v[176:179], v[108:111]
	v_mfma_f32_16x16x32_bf16 v[96:99], v[136:139], v[184:187], v[96:99]
	v_mfma_f32_16x16x32_bf16 v[92:95], v[144:147], v[184:187], v[92:95]
	v_mfma_f32_16x16x32_bf16 v[80:83], v[136:139], v[222:225], v[80:83]
	v_mfma_f32_16x16x32_bf16 v[76:79], v[144:147], v[222:225], v[76:79]
	v_mfma_f32_16x16x32_bf16 v[120:123], v[148:151], v[164:167], v[120:123]
	v_mfma_f32_16x16x32_bf16 v[116:119], v[156:159], v[164:167], v[116:119]
	v_mfma_f32_16x16x32_bf16 v[104:107], v[148:151], v[172:175], v[104:107]
	v_mfma_f32_16x16x32_bf16 v[100:103], v[156:159], v[172:175], v[100:103]
	v_mfma_f32_16x16x32_bf16 v[88:91], v[148:151], v[180:183], v[88:91]
	v_mfma_f32_16x16x32_bf16 v[84:87], v[156:159], v[180:183], v[84:87]
	v_mfma_f32_16x16x32_bf16 v[72:75], v[148:151], v[218:221], v[72:75]
	v_mfma_f32_16x16x32_bf16 v[68:71], v[156:159], v[218:221], v[68:71]
	v_mfma_f32_16x16x32_bf16 v[120:123], v[152:155], v[168:171], v[120:123]
	v_mfma_f32_16x16x32_bf16 v[116:119], v[160:163], v[168:171], v[116:119]
	v_mfma_f32_16x16x32_bf16 v[104:107], v[152:155], v[176:179], v[104:107]
	v_mfma_f32_16x16x32_bf16 v[100:103], v[160:163], v[176:179], v[100:103]
	v_mfma_f32_16x16x32_bf16 v[88:91], v[152:155], v[184:187], v[88:91]
	v_mfma_f32_16x16x32_bf16 v[84:87], v[160:163], v[184:187], v[84:87]
	v_mfma_f32_16x16x32_bf16 v[72:75], v[152:155], v[222:225], v[72:75]
	v_mfma_f32_16x16x32_bf16 v[68:71], v[160:163], v[222:225], v[68:71]
	s_barrier
; #define PG8_STAGE(bufoff, gbase, voff) do { _Pragma("unroll") for (int _i = 0; _i < 2; ++_i) \
;         __builtin_amdgcn_global_load_lds((const unsigned*)((const char*)(gbase) + (voff)[_i]), (PG8_LAS unsigned*)(lds + (bufoff) + ldsw + _i * 8192), 16, 0, 0); } while (0)
; #define PG8_LDA(dst, b, h) do { _Pragma("unroll") for (int m = 0; m < 4; ++m) _Pragma("unroll") for (int k = 0; k < 2; ++k) dst[m][k] = *(const PG8_LAS bf16x8*)(lds + PG8_SA(b, h) + aoff + m * 2048 + k * 1024); } while (0)
; #define PG8_MMA(ai, bj, At, Bt) do { __builtin_amdgcn_s_setprio(1); _Pragma("unroll") for (int m = 0; m < 4; ++m) _Pragma("unroll") for (int n = 0; n < 2; ++n) _Pragma("unroll") for (int k = 0; k < 2; ++k) \
;         acc[ai][bj][m][n] = __builtin_amdgcn_mfma_f32_16x16x32_bf16(Bt[n][k], At[m][k], acc[ai][bj][m][n], 0, 0, 0); __builtin_amdgcn_s_setprio(0); } while (0)
; #define PG8_WAIT_V(n) asm volatile("s_waitcnt vmcnt(" #n ")" ::: "memory")
; #define PG8_WAIT_L(n) asm volatile("s_waitcnt lgkmcnt(" #n ")" ::: "memory")
; #define PG8_BAR __builtin_amdgcn_s_barrier()
; #define PG8_SCHED __builtin_amdgcn_sched_barrier(0)
; template <class Epi, class Sched, bool ALIGN_EPI = false, bool SP2 = false>
; __device__ __forceinline__ void gemm_phase(PG8_LAS unsigned char* lds, const Gemm g, const Sched& S, const Epi& E, int tid_in) {
;     ...
;         for (int t = 0; t < nt; t += 2) {
;     ...
;             PG8_LDA(At, 1, 1); PG8_STAGE(PG8_SB(1, 0), b3, voffB); PG8_STAGE(PG8_SB(1, 1), b3 + hstep, voffB); PG8_STAGE(PG8_SA(1, 0), a3, voffA);
;             PG8_WAIT_V(8); PG8_WAIT_L(0); PG8_BAR; PG8_MMA(1, 0, At, B0); PG8_MMA(1, 1, At, B1); PG8_BAR; PG8_SCHED;
	s_add_i32 s0, s81, s57
	v_lshl_add_u64 v[6:7], v[226:227], 0, s[12:13]
	s_mov_b32 m0, s0
	ds_read_b128 v[164:167], v216 offset:49152
	ds_read_b128 v[168:171], v216 offset:50176
	ds_read_b128 v[172:175], v216 offset:51200
	ds_read_b128 v[176:179], v216 offset:52224
	ds_read_b128 v[180:183], v216 offset:53248
	ds_read_b128 v[184:187], v216 offset:54272
	ds_read_b128 v[218:221], v216 offset:55296
	ds_read_b128 v[222:225], v216 offset:56320
	global_load_lds_dwordx4 v[6:7], off
	s_add_i32 m0, s0, 0x2000
	s_add_u32 s0, s48, 0x40080
	v_lshl_add_u64 v[6:7], v[228:229], 0, s[12:13]
	s_addc_u32 s1, s49, 0
	s_add_i32 s48, s82, s57
	global_load_lds_dwordx4 v[6:7], off
	v_lshl_add_u64 v[6:7], s[0:1], 0, v[190:191]
	s_mov_b32 m0, s48
	s_nop 0
	global_load_lds_dwordx4 v[6:7], off
	v_lshl_add_u64 v[6:7], s[0:1], 0, v[194:195]
	s_add_i32 m0, s48, 0x2000
	s_nop 0
	global_load_lds_dwordx4 v[6:7], off
	v_lshl_add_u64 v[6:7], v[232:233], 0, s[12:13]
	s_mov_b32 m0, s64
	s_nop 0
	global_load_lds_dwordx4 v[6:7], off
	v_lshl_add_u64 v[6:7], v[234:235], 0, s[12:13]
	s_mov_b32 m0, s65
	s_nop 0
	global_load_lds_dwordx4 v[6:7], off
	s_waitcnt vmcnt(8)
	s_waitcnt lgkmcnt(0)
	s_barrier
	v_mfma_f32_16x16x32_bf16 v[64:67], v[132:135], v[164:167], v[64:67]
	v_mfma_f32_16x16x32_bf16 v[60:63], v[140:143], v[164:167], v[60:63]
	v_mfma_f32_16x16x32_bf16 v[48:51], v[132:135], v[172:175], v[48:51]
	v_mfma_f32_16x16x32_bf16 v[44:47], v[140:143], v[172:175], v[44:47]
	v_mfma_f32_16x16x32_bf16 v[32:35], v[132:135], v[180:183], v[32:35]
	v_mfma_f32_16x16x32_bf16 v[28:31], v[140:143], v[180:183], v[28:31]
	v_mfma_f32_16x16x32_bf16 v[16:19], v[132:135], v[218:221], v[16:19]
	v_mfma_f32_16x16x32_bf16 v[12:15], v[140:143], v[218:221], v[12:15]
	v_mfma_f32_16x16x32_bf16 v[64:67], v[136:139], v[168:171], v[64:67]
	v_mfma_f32_16x16x32_bf16 v[60:63], v[144:147], v[168:171], v[60:63]
	v_mfma_f32_16x16x32_bf16 v[48:51], v[136:139], v[176:179], v[48:51]
	v_mfma_f32_16x16x32_bf16 v[44:47], v[144:147], v[176:179], v[44:47]
	v_mfma_f32_16x16x32_bf16 v[32:35], v[136:139], v[184:187], v[32:35]
	v_mfma_f32_16x16x32_bf16 v[28:31], v[144:147], v[184:187], v[28:31]
	v_mfma_f32_16x16x32_bf16 v[16:19], v[136:139], v[222:225], v[16:19]
	v_mfma_f32_16x16x32_bf16 v[12:15], v[144:147], v[222:225], v[12:15]
	v_mfma_f32_16x16x32_bf16 v[56:59], v[148:151], v[164:167], v[56:59]
	v_mfma_f32_16x16x32_bf16 v[52:55], v[156:159], v[164:167], v[52:55]
	v_mfma_f32_16x16x32_bf16 v[40:43], v[148:151], v[172:175], v[40:43]
	v_mfma_f32_16x16x32_bf16 v[36:39], v[156:159], v[172:175], v[36:39]
	v_mfma_f32_16x16x32_bf16 v[24:27], v[148:151], v[180:183], v[24:27]
	v_mfma_f32_16x16x32_bf16 v[20:23], v[156:159], v[180:183], v[20:23]
	v_mfma_f32_16x16x32_bf16 v[6:9], v[148:151], v[218:221], v[8:11]
	v_mfma_f32_16x16x32_bf16 v[2:5], v[156:159], v[218:221], v[2:5]
	v_mfma_f32_16x16x32_bf16 v[56:59], v[152:155], v[168:171], v[56:59]
	v_mfma_f32_16x16x32_bf16 v[52:55], v[160:163], v[168:171], v[52:55]
	v_mfma_f32_16x16x32_bf16 v[40:43], v[152:155], v[176:179], v[40:43]
	v_mfma_f32_16x16x32_bf16 v[36:39], v[160:163], v[176:179], v[36:39]
	v_mfma_f32_16x16x32_bf16 v[24:27], v[152:155], v[184:187], v[24:27]
	v_mfma_f32_16x16x32_bf16 v[20:23], v[160:163], v[184:187], v[20:23]
	v_mfma_f32_16x16x32_bf16 v[8:11], v[152:155], v[222:225], v[6:9]
	v_mfma_f32_16x16x32_bf16 v[4:7], v[160:163], v[222:225], v[2:5]
	s_barrier
	s_add_i32 s80, s80, 2
	s_add_u32 s46, s46, 0x100
	s_addc_u32 s47, s47, 0
	s_cmp_gt_u32 s80, 13
	s_cbranch_scc1 .LBB0_1068

; #define PG8_STAGE(bufoff, gbase, voff) do { _Pragma("unroll") for (int _i = 0; _i < 2; ++_i) \
;         __builtin_amdgcn_global_load_lds((const unsigned*)((const char*)(gbase) + (voff)[_i]), (PG8_LAS unsigned*)(lds + (bufoff) + ldsw + _i * 8192), 16, 0, 0); } while (0)
; #define PG8_LDA(dst, b, h) do { _Pragma("unroll") for (int m = 0; m < 4; ++m) _Pragma("unroll") for (int k = 0; k < 2; ++k) dst[m][k] = *(const PG8_LAS bf16x8*)(lds + PG8_SA(b, h) + aoff + m * 2048 + k * 1024); } while (0)
; #define PG8_LDB(dst, b, h) do { _Pragma("unroll") for (int n = 0; n < 2; ++n) _Pragma("unroll") for (int k = 0; k < 2; ++k) dst[n][k] = *(const PG8_LAS bf16x8*)(lds + PG8_SB(b, h) + boff + n * 2048 + k * 1024); } while (0)
; #define PG8_WAIT_V(n) asm volatile("s_waitcnt vmcnt(" #n ")" ::: "memory")
; template <class Epi, class Sched, bool ALIGN_EPI = false, bool SP2 = false>
; __device__ __forceinline__ void gemm_phase(PG8_LAS unsigned char* lds, const Gemm g, const Sched& S, const Epi& E, int tid_in) {
;     ...
;             const char* a1 = cA + (size_t)(t + 1) * kstep;
;             const char* a2 = last ? nA : cA + (size_t)(t + 2) * kstep; const char* b2 = last ? nB : cB + (size_t)(t + 2) * kstep;
;             const char* a3 = a2 + kstep; const char* b3 = b2 + kstep;
;             if (last && has_next) S.a_ready(nxt);
;             if constexpr (SP2) {
;             PG8_LDB(B0, 0, 0); PG8_LDB(B1, 0, 1); PG8_SCHED; PG8_LDA(At, 0, 0); PG8_STAGE(PG8_SA(1, 1), a1 + hstep, voffA);
;             PG8_WAIT_V(8); PG8_WAIT_L(0); PG8_BAR; PG8_MMA(0, 0, At, B0); PG8_MMA(0, 1, At, B1); PG8_BAR; PG8_SCHED;
;             PG8_LDA(At, 0, 1); PG8_STAGE(PG8_SB(0, 0), b2, voffB); PG8_STAGE(PG8_SB(0, 1), b2 + hstep, voffB); PG8_STAGE(PG8_SA(0, 0), a2, voffA);
;             PG8_WAIT_V(8); PG8_WAIT_L(0); PG8_BAR; PG8_MMA(1, 0, At, B0); PG8_MMA(1, 1, At, B1); PG8_BAR; PG8_SCHED;
;             PG8_LDB(B0, 1, 0); PG8_LDB(B1, 1, 1); PG8_SCHED; PG8_LDA(At, 1, 0); PG8_STAGE(PG8_SA(0, 1), a2 + hstep, voffA);
;             PG8_WAIT_V(8); PG8_WAIT_L(0); PG8_BAR; PG8_MMA(0, 0, At, B0); PG8_MMA(0, 1, At, B1); PG8_BAR; PG8_SCHED;
;             PG8_LDA(At, 1, 1); PG8_STAGE(PG8_SB(1, 0), b3, voffB); PG8_STAGE(PG8_SB(1, 1), b3 + hstep, voffB); PG8_STAGE(PG8_SA(1, 0), a3, voffA);
;             PG8_WAIT_V(8); PG8_WAIT_L(0); PG8_BAR; PG8_MMA(1, 0, At, B0); PG8_MMA(1, 1, At, B1); PG8_BAR; PG8_SCHED;
.LBB0_1148:
	s_add_u32 s34, s30, 0xfffc0080
	s_addc_u32 s35, s31, -1
	s_cmp_eq_u32 s60, 12
	s_cselect_b32 s37, s23, s35
	s_cselect_b32 s36, s29, s34
	s_cselect_b32 s35, s21, s59
	s_cselect_b32 s34, s57, s58
	s_add_i32 m0, s1, 0xc000
	ds_read_b128 v[128:131], v191
	global_load_lds_dwordx4 v160, s[30:31]
	s_add_i32 m0, s1, 0xe000
	ds_read_b128 v[132:135], v191 offset:1024
	global_load_lds_dwordx4 v162, s[30:31]
	ds_read_b128 v[136:139], v191 offset:2048
	ds_read_b128 v[140:143], v191 offset:3072
	ds_read_b128 v[144:147], v192
	ds_read_b128 v[148:151], v192 offset:1024
	ds_read_b128 v[168:171], v192 offset:2048
	ds_read_b128 v[172:175], v192 offset:3072
	ds_read_b128 v[176:179], v193
	ds_read_b128 v[180:183], v193 offset:1024
	ds_read_b128 v[194:197], v193 offset:2048
	ds_read_b128 v[198:201], v193 offset:3072
	ds_read_b128 v[202:205], v193 offset:4096
	ds_read_b128 v[206:209], v193 offset:5120
	ds_read_b128 v[210:213], v193 offset:6144
	ds_read_b128 v[214:217], v193 offset:7168
	s_waitcnt vmcnt(8)
	s_waitcnt lgkmcnt(0)
	s_barrier
	v_mfma_f32_16x16x32_bf16 v[124:127], v[128:131], v[176:179], v[124:127]
	v_mfma_f32_16x16x32_bf16 v[120:123], v[136:139], v[176:179], v[120:123]
	v_mfma_f32_16x16x32_bf16 v[108:111], v[128:131], v[194:197], v[108:111]
	v_mfma_f32_16x16x32_bf16 v[104:107], v[136:139], v[194:197], v[104:107]
	v_mfma_f32_16x16x32_bf16 v[92:95], v[128:131], v[202:205], v[92:95]
	v_mfma_f32_16x16x32_bf16 v[88:91], v[136:139], v[202:205], v[88:91]
	v_mfma_f32_16x16x32_bf16 v[76:79], v[128:131], v[210:213], v[76:79]
	v_mfma_f32_16x16x32_bf16 v[72:75], v[136:139], v[210:213], v[72:75]
	v_mfma_f32_16x16x32_bf16 v[124:127], v[132:135], v[180:183], v[124:127]
	v_mfma_f32_16x16x32_bf16 v[120:123], v[140:143], v[180:183], v[120:123]
	v_mfma_f32_16x16x32_bf16 v[108:111], v[132:135], v[198:201], v[108:111]
	v_mfma_f32_16x16x32_bf16 v[104:107], v[140:143], v[198:201], v[104:107]
	v_mfma_f32_16x16x32_bf16 v[92:95], v[132:135], v[206:209], v[92:95]
	v_mfma_f32_16x16x32_bf16 v[88:91], v[140:143], v[206:209], v[88:91]
	v_mfma_f32_16x16x32_bf16 v[76:79], v[132:135], v[214:217], v[76:79]
	v_mfma_f32_16x16x32_bf16 v[72:75], v[140:143], v[214:217], v[72:75]
	v_mfma_f32_16x16x32_bf16 v[116:119], v[144:147], v[176:179], v[116:119]
	v_mfma_f32_16x16x32_bf16 v[112:115], v[168:171], v[176:179], v[112:115]
	v_mfma_f32_16x16x32_bf16 v[100:103], v[144:147], v[194:197], v[100:103]
	v_mfma_f32_16x16x32_bf16 v[96:99], v[168:171], v[194:197], v[96:99]
	v_mfma_f32_16x16x32_bf16 v[84:87], v[144:147], v[202:205], v[84:87]
	v_mfma_f32_16x16x32_bf16 v[80:83], v[168:171], v[202:205], v[80:83]
	v_mfma_f32_16x16x32_bf16 v[68:71], v[144:147], v[210:213], v[68:71]
	v_mfma_f32_16x16x32_bf16 v[64:67], v[168:171], v[210:213], v[64:67]
	v_mfma_f32_16x16x32_bf16 v[116:119], v[148:151], v[180:183], v[116:119]
	v_mfma_f32_16x16x32_bf16 v[112:115], v[172:175], v[180:183], v[112:115]
	v_mfma_f32_16x16x32_bf16 v[100:103], v[148:151], v[198:201], v[100:103]
	v_mfma_f32_16x16x32_bf16 v[96:99], v[172:175], v[198:201], v[96:99]
	v_mfma_f32_16x16x32_bf16 v[84:87], v[148:151], v[206:209], v[84:87]
	v_mfma_f32_16x16x32_bf16 v[80:83], v[172:175], v[206:209], v[80:83]
	v_mfma_f32_16x16x32_bf16 v[68:71], v[148:151], v[214:217], v[68:71]
	v_mfma_f32_16x16x32_bf16 v[64:67], v[172:175], v[214:217], v[64:67]
	s_barrier
	s_add_u32 s98, s34, s16
	s_addc_u32 s99, s35, s17
	s_add_u32 s100, s36, s16
	s_addc_u32 s101, s37, s17
	s_add_i32 s61, s54, s0
	s_mov_b32 m0, s61
	ds_read_b128 v[176:179], v193 offset:16384
	global_load_lds_dwordx4 v154, s[34:35]
	s_add_i32 m0, s61, 0x2000
	s_add_u32 s62, s34, 0x40000
	s_addc_u32 s63, s35, 0
	s_add_i32 s61, s55, s0
	global_load_lds_dwordx4 v158, s[34:35]
	s_mov_b32 m0, s61
	ds_read_b128 v[180:183], v193 offset:17408
	global_load_lds_dwordx4 v154, s[62:63]
	s_add_i32 m0, s61, 0x2000
	ds_read_b128 v[194:197], v193 offset:18432
	global_load_lds_dwordx4 v158, s[62:63]
	s_mov_b32 m0, s1
	ds_read_b128 v[198:201], v193 offset:19456
	global_load_lds_dwordx4 v152, s[36:37]
	s_mov_b32 m0, s46
	ds_read_b128 v[202:205], v193 offset:20480
	global_load_lds_dwordx4 v156, s[36:37]
	ds_read_b128 v[206:209], v193 offset:21504
	ds_read_b128 v[210:213], v193 offset:22528
	ds_read_b128 v[214:217], v193 offset:23552
	s_waitcnt vmcnt(8)
	s_waitcnt lgkmcnt(0)
	s_barrier
	v_mfma_f32_16x16x32_bf16 v[60:63], v[128:131], v[176:179], v[60:63]
	v_mfma_f32_16x16x32_bf16 v[56:59], v[136:139], v[176:179], v[56:59]
	v_mfma_f32_16x16x32_bf16 v[44:47], v[128:131], v[194:197], v[44:47]
	v_mfma_f32_16x16x32_bf16 v[40:43], v[136:139], v[194:197], v[40:43]
	v_mfma_f32_16x16x32_bf16 v[28:31], v[128:131], v[202:205], v[28:31]
	v_mfma_f32_16x16x32_bf16 v[24:27], v[136:139], v[202:205], v[24:27]
	v_mfma_f32_16x16x32_bf16 v[12:15], v[128:131], v[210:213], v[12:15]
	v_mfma_f32_16x16x32_bf16 v[8:11], v[136:139], v[210:213], v[8:11]
	v_mfma_f32_16x16x32_bf16 v[60:63], v[132:135], v[180:183], v[60:63]
	v_mfma_f32_16x16x32_bf16 v[56:59], v[140:143], v[180:183], v[56:59]
	v_mfma_f32_16x16x32_bf16 v[44:47], v[132:135], v[198:201], v[44:47]
	v_mfma_f32_16x16x32_bf16 v[40:43], v[140:143], v[198:201], v[40:43]
	v_mfma_f32_16x16x32_bf16 v[28:31], v[132:135], v[206:209], v[28:31]
	v_mfma_f32_16x16x32_bf16 v[24:27], v[140:143], v[206:209], v[24:27]
	v_mfma_f32_16x16x32_bf16 v[12:15], v[132:135], v[214:217], v[12:15]
	v_mfma_f32_16x16x32_bf16 v[8:11], v[140:143], v[214:217], v[8:11]
	v_mfma_f32_16x16x32_bf16 v[52:55], v[144:147], v[176:179], v[52:55]
	v_mfma_f32_16x16x32_bf16 v[48:51], v[168:171], v[176:179], v[48:51]
	v_mfma_f32_16x16x32_bf16 v[36:39], v[144:147], v[194:197], v[36:39]
	v_mfma_f32_16x16x32_bf16 v[32:35], v[168:171], v[194:197], v[32:35]
	v_mfma_f32_16x16x32_bf16 v[20:23], v[144:147], v[202:205], v[20:23]
	v_mfma_f32_16x16x32_bf16 v[16:19], v[168:171], v[202:205], v[16:19]
	v_mfma_f32_16x16x32_bf16 v[4:7], v[144:147], v[210:213], v[4:7]
	v_mfma_f32_16x16x32_bf16 v[0:3], v[168:171], v[210:213], v[0:3]
	v_mfma_f32_16x16x32_bf16 v[52:55], v[148:151], v[180:183], v[52:55]
	v_mfma_f32_16x16x32_bf16 v[48:51], v[172:175], v[180:183], v[48:51]
	v_mfma_f32_16x16x32_bf16 v[36:39], v[148:151], v[198:201], v[36:39]
	v_mfma_f32_16x16x32_bf16 v[32:35], v[172:175], v[198:201], v[32:35]
	v_mfma_f32_16x16x32_bf16 v[20:23], v[148:151], v[206:209], v[20:23]
	v_mfma_f32_16x16x32_bf16 v[16:19], v[172:175], v[206:209], v[16:19]
	v_mfma_f32_16x16x32_bf16 v[4:7], v[148:151], v[214:217], v[4:7]
	v_mfma_f32_16x16x32_bf16 v[0:3], v[172:175], v[214:217], v[0:3]
	s_barrier
; #define PG8_STAGE(bufoff, gbase, voff) do { _Pragma("unroll") for (int _i = 0; _i < 2; ++_i) \
;         __builtin_amdgcn_global_load_lds((const unsigned*)((const char*)(gbase) + (voff)[_i]), (PG8_LAS unsigned*)(lds + (bufoff) + ldsw + _i * 8192), 16, 0, 0); } while (0)
; #define PG8_LDA(dst, b, h) do { _Pragma("unroll") for (int m = 0; m < 4; ++m) _Pragma("unroll") for (int k = 0; k < 2; ++k) dst[m][k] = *(const PG8_LAS bf16x8*)(lds + PG8_SA(b, h) + aoff + m * 2048 + k * 1024); } while (0)
; #define PG8_LDB(dst, b, h) do { _Pragma("unroll") for (int n = 0; n < 2; ++n) _Pragma("unroll") for (int k = 0; k < 2; ++k) dst[n][k] = *(const PG8_LAS bf16x8*)(lds + PG8_SB(b, h) + boff + n * 2048 + k * 1024); } while (0)
; #define PG8_WAIT_V(n) asm volatile("s_waitcnt vmcnt(" #n ")" ::: "memory")
; template <class Epi, class Sched, bool ALIGN_EPI = false, bool SP2 = false>
; __device__ __forceinline__ void gemm_phase(PG8_LAS unsigned char* lds, const Gemm g, const Sched& S, const Epi& E, int tid_in) {
;     ...
;             const char* a1 = cA + (size_t)(t + 1) * kstep;
;             const char* a2 = last ? nA : cA + (size_t)(t + 2) * kstep; const char* b2 = last ? nB : cB + (size_t)(t + 2) * kstep;
;             const char* a3 = a2 + kstep; const char* b3 = b2 + kstep;
;             if (last && has_next) S.a_ready(nxt);
;             if constexpr (SP2) {
;             PG8_LDB(B0, 0, 0); PG8_LDB(B1, 0, 1); PG8_SCHED; PG8_LDA(At, 0, 0); PG8_STAGE(PG8_SA(1, 1), a1 + hstep, voffA);
;             PG8_WAIT_V(8); PG8_WAIT_L(0); PG8_BAR; PG8_MMA(0, 0, At, B0); PG8_MMA(0, 1, At, B1); PG8_BAR; PG8_SCHED;
;             PG8_LDA(At, 0, 1); PG8_STAGE(PG8_SB(0, 0), b2, voffB); PG8_STAGE(PG8_SB(0, 1), b2 + hstep, voffB); PG8_STAGE(PG8_SA(0, 0), a2, voffA);
;             PG8_WAIT_V(8); PG8_WAIT_L(0); PG8_BAR; PG8_MMA(1, 0, At, B0); PG8_MMA(1, 1, At, B1); PG8_BAR; PG8_SCHED;
;             PG8_LDB(B0, 1, 0); PG8_LDB(B1, 1, 1); PG8_SCHED; PG8_LDA(At, 1, 0); PG8_STAGE(PG8_SA(0, 1), a2 + hstep, voffA);
;             PG8_WAIT_V(8); PG8_WAIT_L(0); PG8_BAR; PG8_MMA(0, 0, At, B0); PG8_MMA(0, 1, At, B1); PG8_BAR; PG8_SCHED;
;             PG8_LDA(At, 1, 1); PG8_STAGE(PG8_SB(1, 0), b3, voffB); PG8_STAGE(PG8_SB(1, 1), b3 + hstep, voffB); PG8_STAGE(PG8_SA(1, 0), a3, voffA);
;             PG8_WAIT_V(8); PG8_WAIT_L(0); PG8_BAR; PG8_MMA(1, 0, At, B0); PG8_MMA(1, 1, At, B1); PG8_BAR; PG8_SCHED;
	s_add_i32 s61, 0, 0x18000
	s_add_i32 s62, 0, 0x1c000
	s_add_u32 s36, s36, 0x40000
	s_addc_u32 s37, s37, 0
	s_mov_b32 m0, s47
	s_nop 0
	global_load_lds_dwordx4 v152, s[36:37]
	s_mov_b32 m0, s48
	s_nop 0
	global_load_lds_dwordx4 v156, s[36:37]
	v_add_u32_e32 v140, s61, v187
	v_add_u32_e32 v172, s62, v187
	ds_read_b128 v[128:131], v140
	ds_read_b128 v[132:135], v140 offset:1024
	ds_read_b128 v[136:139], v140 offset:2048
	ds_read_b128 v[140:143], v140 offset:3072
	ds_read_b128 v[144:147], v172
	ds_read_b128 v[148:151], v172 offset:1024
	ds_read_b128 v[168:171], v172 offset:2048
	ds_read_b128 v[172:175], v172 offset:3072
	ds_read_b128 v[176:179], v193 offset:32768
	ds_read_b128 v[180:183], v193 offset:33792
	ds_read_b128 v[194:197], v193 offset:34816
	ds_read_b128 v[198:201], v193 offset:35840
	ds_read_b128 v[202:205], v193 offset:36864
	ds_read_b128 v[206:209], v193 offset:37888
	ds_read_b128 v[210:213], v193 offset:38912
	ds_read_b128 v[214:217], v193 offset:39936
	s_waitcnt vmcnt(8)
	s_waitcnt lgkmcnt(0)
	s_barrier
	v_mfma_f32_16x16x32_bf16 v[124:127], v[128:131], v[176:179], v[124:127]
	v_mfma_f32_16x16x32_bf16 v[120:123], v[136:139], v[176:179], v[120:123]
	v_mfma_f32_16x16x32_bf16 v[108:111], v[128:131], v[194:197], v[108:111]
	v_mfma_f32_16x16x32_bf16 v[104:107], v[136:139], v[194:197], v[104:107]
	v_mfma_f32_16x16x32_bf16 v[92:95], v[128:131], v[202:205], v[92:95]
	v_mfma_f32_16x16x32_bf16 v[88:91], v[136:139], v[202:205], v[88:91]
	v_mfma_f32_16x16x32_bf16 v[76:79], v[128:131], v[210:213], v[76:79]
	v_mfma_f32_16x16x32_bf16 v[72:75], v[136:139], v[210:213], v[72:75]
	v_mfma_f32_16x16x32_bf16 v[124:127], v[132:135], v[180:183], v[124:127]
	v_mfma_f32_16x16x32_bf16 v[120:123], v[140:143], v[180:183], v[120:123]
	v_mfma_f32_16x16x32_bf16 v[108:111], v[132:135], v[198:201], v[108:111]
	v_mfma_f32_16x16x32_bf16 v[104:107], v[140:143], v[198:201], v[104:107]
	v_mfma_f32_16x16x32_bf16 v[92:95], v[132:135], v[206:209], v[92:95]
	v_mfma_f32_16x16x32_bf16 v[88:91], v[140:143], v[206:209], v[88:91]
	v_mfma_f32_16x16x32_bf16 v[76:79], v[132:135], v[214:217], v[76:79]
	v_mfma_f32_16x16x32_bf16 v[72:75], v[140:143], v[214:217], v[72:75]
	v_mfma_f32_16x16x32_bf16 v[116:119], v[144:147], v[176:179], v[116:119]
	v_mfma_f32_16x16x32_bf16 v[112:115], v[168:171], v[176:179], v[112:115]
	v_mfma_f32_16x16x32_bf16 v[100:103], v[144:147], v[194:197], v[100:103]
	v_mfma_f32_16x16x32_bf16 v[96:99], v[168:171], v[194:197], v[96:99]
	v_mfma_f32_16x16x32_bf16 v[84:87], v[144:147], v[202:205], v[84:87]
	v_mfma_f32_16x16x32_bf16 v[80:83], v[168:171], v[202:205], v[80:83]
	v_mfma_f32_16x16x32_bf16 v[68:71], v[144:147], v[210:213], v[68:71]
	v_mfma_f32_16x16x32_bf16 v[64:67], v[168:171], v[210:213], v[64:67]
	v_mfma_f32_16x16x32_bf16 v[116:119], v[148:151], v[180:183], v[116:119]
	v_mfma_f32_16x16x32_bf16 v[112:115], v[172:175], v[180:183], v[112:115]
	v_mfma_f32_16x16x32_bf16 v[100:103], v[148:151], v[198:201], v[100:103]
	v_mfma_f32_16x16x32_bf16 v[96:99], v[172:175], v[198:201], v[96:99]
	v_mfma_f32_16x16x32_bf16 v[84:87], v[148:151], v[206:209], v[84:87]
	v_mfma_f32_16x16x32_bf16 v[80:83], v[172:175], v[206:209], v[80:83]
	v_mfma_f32_16x16x32_bf16 v[68:71], v[148:151], v[214:217], v[68:71]
	v_mfma_f32_16x16x32_bf16 v[64:67], v[172:175], v[214:217], v[64:67]
	s_barrier
	s_add_i32 s36, s61, s0
	s_mov_b32 m0, s36
	ds_read_b128 v[176:179], v193 offset:49152
	global_load_lds_dwordx4 v154, s[98:99]
	s_add_i32 m0, s36, 0x2000
	s_add_u32 s34, s34, 0x40080
	s_addc_u32 s35, s35, 0
	s_add_i32 s36, s62, s0
	global_load_lds_dwordx4 v158, s[98:99]
	s_mov_b32 m0, s36
	ds_read_b128 v[180:183], v193 offset:50176
	global_load_lds_dwordx4 v154, s[34:35]
	s_add_i32 m0, s36, 0x2000
	ds_read_b128 v[194:197], v193 offset:51200
	global_load_lds_dwordx4 v158, s[34:35]
	s_mov_b32 m0, s50
	ds_read_b128 v[198:201], v193 offset:52224
	global_load_lds_dwordx4 v152, s[100:101]
	s_mov_b32 m0, s51
	ds_read_b128 v[202:205], v193 offset:53248
	global_load_lds_dwordx4 v156, s[100:101]
	ds_read_b128 v[206:209], v193 offset:54272
	ds_read_b128 v[210:213], v193 offset:55296
	ds_read_b128 v[214:217], v193 offset:56320
	s_waitcnt vmcnt(8)
	s_waitcnt lgkmcnt(0)
	s_barrier
	v_mfma_f32_16x16x32_bf16 v[60:63], v[128:131], v[176:179], v[60:63]
	v_mfma_f32_16x16x32_bf16 v[56:59], v[136:139], v[176:179], v[56:59]
	v_mfma_f32_16x16x32_bf16 v[44:47], v[128:131], v[194:197], v[44:47]
	v_mfma_f32_16x16x32_bf16 v[40:43], v[136:139], v[194:197], v[40:43]
	v_mfma_f32_16x16x32_bf16 v[28:31], v[128:131], v[202:205], v[28:31]
	v_mfma_f32_16x16x32_bf16 v[24:27], v[136:139], v[202:205], v[24:27]
	v_mfma_f32_16x16x32_bf16 v[12:15], v[128:131], v[210:213], v[12:15]
	v_mfma_f32_16x16x32_bf16 v[8:11], v[136:139], v[210:213], v[8:11]
	v_mfma_f32_16x16x32_bf16 v[60:63], v[132:135], v[180:183], v[60:63]
	v_mfma_f32_16x16x32_bf16 v[56:59], v[140:143], v[180:183], v[56:59]
	v_mfma_f32_16x16x32_bf16 v[44:47], v[132:135], v[198:201], v[44:47]
	v_mfma_f32_16x16x32_bf16 v[40:43], v[140:143], v[198:201], v[40:43]
	v_mfma_f32_16x16x32_bf16 v[28:31], v[132:135], v[206:209], v[28:31]
	v_mfma_f32_16x16x32_bf16 v[24:27], v[140:143], v[206:209], v[24:27]
	v_mfma_f32_16x16x32_bf16 v[12:15], v[132:135], v[214:217], v[12:15]
	v_mfma_f32_16x16x32_bf16 v[8:11], v[140:143], v[214:217], v[8:11]
	v_mfma_f32_16x16x32_bf16 v[52:55], v[144:147], v[176:179], v[52:55]
	v_mfma_f32_16x16x32_bf16 v[48:51], v[168:171], v[176:179], v[48:51]
	v_mfma_f32_16x16x32_bf16 v[36:39], v[144:147], v[194:197], v[36:39]
	v_mfma_f32_16x16x32_bf16 v[32:35], v[168:171], v[194:197], v[32:35]
	v_mfma_f32_16x16x32_bf16 v[20:23], v[144:147], v[202:205], v[20:23]
	v_mfma_f32_16x16x32_bf16 v[16:19], v[168:171], v[202:205], v[16:19]
	v_mfma_f32_16x16x32_bf16 v[4:7], v[144:147], v[210:213], v[4:7]
	v_mfma_f32_16x16x32_bf16 v[0:3], v[168:171], v[210:213], v[0:3]
	v_mfma_f32_16x16x32_bf16 v[52:55], v[148:151], v[180:183], v[52:55]
	v_mfma_f32_16x16x32_bf16 v[48:51], v[172:175], v[180:183], v[48:51]
	v_mfma_f32_16x16x32_bf16 v[36:39], v[148:151], v[198:201], v[36:39]
	v_mfma_f32_16x16x32_bf16 v[32:35], v[172:175], v[198:201], v[32:35]
	v_mfma_f32_16x16x32_bf16 v[20:23], v[148:151], v[206:209], v[20:23]
	v_mfma_f32_16x16x32_bf16 v[16:19], v[172:175], v[206:209], v[16:19]
	v_mfma_f32_16x16x32_bf16 v[4:7], v[148:151], v[214:217], v[4:7]
	v_mfma_f32_16x16x32_bf16 v[0:3], v[172:175], v[214:217], v[0:3]
	s_barrier
	s_add_i32 s60, s60, 2
	s_add_u32 s30, s30, 0x100
	s_addc_u32 s31, s31, 0
	s_add_u32 s58, s58, 0x100
	s_addc_u32 s59, s59, 0
	s_cmp_gt_u32 s60, 13
	s_cbranch_scc0 .LBB0_1148
	s_and_b64 vcc, exec, s[18:19]
	s_cbranch_vccz .LBB0_1151
	s_barrier

; #define PG8_STAGE(bufoff, gbase, voff) do { _Pragma("unroll") for (int _i = 0; _i < 2; ++_i) \
;         __builtin_amdgcn_global_load_lds((const unsigned*)((const char*)(gbase) + (voff)[_i]), (PG8_LAS unsigned*)(lds + (bufoff) + ldsw + _i * 8192), 16, 0, 0); } while (0)
; #define PG8_LDA(dst, b, h) do { _Pragma("unroll") for (int m = 0; m < 4; ++m) _Pragma("unroll") for (int k = 0; k < 2; ++k) dst[m][k] = *(const PG8_LAS bf16x8*)(lds + PG8_SA(b, h) + aoff + m * 2048 + k * 1024); } while (0)
; #define PG8_LDB(dst, b, h) do { _Pragma("unroll") for (int n = 0; n < 2; ++n) _Pragma("unroll") for (int k = 0; k < 2; ++k) dst[n][k] = *(const PG8_LAS bf16x8*)(lds + PG8_SB(b, h) + boff + n * 2048 + k * 1024); } while (0)
; #define PG8_WAIT_V(n) asm volatile("s_waitcnt vmcnt(" #n ")" ::: "memory")
; template <class Epi, class Sched, bool ALIGN_EPI = false, bool SP2 = false>
; __device__ __forceinline__ void gemm_phase(PG8_LAS unsigned char* lds, const Gemm g, const Sched& S, const Epi& E, int tid_in) {
;     ...
;             const char* a1 = cA + (size_t)(t + 1) * kstep;
;             const char* a2 = last ? nA : cA + (size_t)(t + 2) * kstep; const char* b2 = last ? nB : cB + (size_t)(t + 2) * kstep;
;             const char* a3 = a2 + kstep; const char* b3 = b2 + kstep;
;             if (last && has_next) S.a_ready(nxt);
;             if constexpr (SP2) {
;             PG8_LDB(B0, 0, 0); PG8_LDB(B1, 0, 1); PG8_SCHED; PG8_LDA(At, 0, 0); PG8_STAGE(PG8_SA(1, 1), a1 + hstep, voffA);
;             PG8_WAIT_V(8); PG8_WAIT_L(0); PG8_BAR; PG8_MMA(0, 0, At, B0); PG8_MMA(0, 1, At, B1); PG8_BAR; PG8_SCHED;
;             PG8_LDA(At, 0, 1); PG8_STAGE(PG8_SB(0, 0), b2, voffB); PG8_STAGE(PG8_SB(0, 1), b2 + hstep, voffB); PG8_STAGE(PG8_SA(0, 0), a2, voffA);
;             PG8_WAIT_V(8); PG8_WAIT_L(0); PG8_BAR; PG8_MMA(1, 0, At, B0); PG8_MMA(1, 1, At, B1); PG8_BAR; PG8_SCHED;
;             PG8_LDB(B0, 1, 0); PG8_LDB(B1, 1, 1); PG8_SCHED; PG8_LDA(At, 1, 0); PG8_STAGE(PG8_SA(0, 1), a2 + hstep, voffA);
;             PG8_WAIT_V(8); PG8_WAIT_L(0); PG8_BAR; PG8_MMA(0, 0, At, B0); PG8_MMA(0, 1, At, B1); PG8_BAR; PG8_SCHED;
;             PG8_LDA(At, 1, 1); PG8_STAGE(PG8_SB(1, 0), b3, voffB); PG8_STAGE(PG8_SB(1, 1), b3 + hstep, voffB); PG8_STAGE(PG8_SA(1, 0), a3, voffA);
;             PG8_WAIT_V(8); PG8_WAIT_L(0); PG8_BAR; PG8_MMA(1, 0, At, B0); PG8_MMA(1, 1, At, B1); PG8_BAR; PG8_SCHED;
.LBB0_1238:
	s_add_u32 s26, s24, 0xfffc0080
	s_addc_u32 s27, s25, -1
	s_cmp_eq_u32 s58, 12
	s_cselect_b32 s29, s17, s27
	s_cselect_b32 s28, s54, s26
	s_cselect_b32 s27, s15, s57
	s_cselect_b32 s26, s55, s56
	s_add_i32 m0, s23, 0xc000
	ds_read_b128 v[144:147], v154
	global_load_lds_dwordx4 v136, s[24:25]
	s_add_i32 m0, s23, 0xe000
	ds_read_b128 v[158:161], v154 offset:1024
	global_load_lds_dwordx4 v138, s[24:25]
	ds_read_b128 v[162:165], v154 offset:2048
	ds_read_b128 v[166:169], v154 offset:3072
	ds_read_b128 v[170:173], v155
	ds_read_b128 v[174:177], v155 offset:1024
	ds_read_b128 v[178:181], v155 offset:2048
	ds_read_b128 v[182:185], v155 offset:3072
	ds_read_b128 v[186:189], v156
	ds_read_b128 v[190:193], v156 offset:1024
	ds_read_b128 v[194:197], v156 offset:2048
	ds_read_b128 v[198:201], v156 offset:3072
	ds_read_b128 v[202:205], v156 offset:4096
	ds_read_b128 v[206:209], v156 offset:5120
	ds_read_b128 v[210:213], v156 offset:6144
	ds_read_b128 v[214:217], v156 offset:7168
	s_waitcnt vmcnt(8)
	s_waitcnt lgkmcnt(0)
	s_barrier
	v_mfma_f32_16x16x32_bf16 v[124:127], v[144:147], v[186:189], v[124:127]
	v_mfma_f32_16x16x32_bf16 v[120:123], v[162:165], v[186:189], v[120:123]
	v_mfma_f32_16x16x32_bf16 v[108:111], v[144:147], v[194:197], v[108:111]
	v_mfma_f32_16x16x32_bf16 v[104:107], v[162:165], v[194:197], v[104:107]
	v_mfma_f32_16x16x32_bf16 v[92:95], v[144:147], v[202:205], v[92:95]
	v_mfma_f32_16x16x32_bf16 v[88:91], v[162:165], v[202:205], v[88:91]
	v_mfma_f32_16x16x32_bf16 v[76:79], v[144:147], v[210:213], v[76:79]
	v_mfma_f32_16x16x32_bf16 v[72:75], v[162:165], v[210:213], v[72:75]
	v_mfma_f32_16x16x32_bf16 v[124:127], v[158:161], v[190:193], v[124:127]
	v_mfma_f32_16x16x32_bf16 v[120:123], v[166:169], v[190:193], v[120:123]
	v_mfma_f32_16x16x32_bf16 v[108:111], v[158:161], v[198:201], v[108:111]
	v_mfma_f32_16x16x32_bf16 v[104:107], v[166:169], v[198:201], v[104:107]
	v_mfma_f32_16x16x32_bf16 v[92:95], v[158:161], v[206:209], v[92:95]
	v_mfma_f32_16x16x32_bf16 v[88:91], v[166:169], v[206:209], v[88:91]
	v_mfma_f32_16x16x32_bf16 v[76:79], v[158:161], v[214:217], v[76:79]
	v_mfma_f32_16x16x32_bf16 v[72:75], v[166:169], v[214:217], v[72:75]
	v_mfma_f32_16x16x32_bf16 v[116:119], v[170:173], v[186:189], v[116:119]
	v_mfma_f32_16x16x32_bf16 v[112:115], v[178:181], v[186:189], v[112:115]
	v_mfma_f32_16x16x32_bf16 v[100:103], v[170:173], v[194:197], v[100:103]
	v_mfma_f32_16x16x32_bf16 v[96:99], v[178:181], v[194:197], v[96:99]
	v_mfma_f32_16x16x32_bf16 v[84:87], v[170:173], v[202:205], v[84:87]
	v_mfma_f32_16x16x32_bf16 v[80:83], v[178:181], v[202:205], v[80:83]
	v_mfma_f32_16x16x32_bf16 v[68:71], v[170:173], v[210:213], v[68:71]
	v_mfma_f32_16x16x32_bf16 v[64:67], v[178:181], v[210:213], v[64:67]
	v_mfma_f32_16x16x32_bf16 v[116:119], v[174:177], v[190:193], v[116:119]
	v_mfma_f32_16x16x32_bf16 v[112:115], v[182:185], v[190:193], v[112:115]
	v_mfma_f32_16x16x32_bf16 v[100:103], v[174:177], v[198:201], v[100:103]
	v_mfma_f32_16x16x32_bf16 v[96:99], v[182:185], v[198:201], v[96:99]
	v_mfma_f32_16x16x32_bf16 v[84:87], v[174:177], v[206:209], v[84:87]
	v_mfma_f32_16x16x32_bf16 v[80:83], v[182:185], v[206:209], v[80:83]
	v_mfma_f32_16x16x32_bf16 v[68:71], v[174:177], v[214:217], v[68:71]
	v_mfma_f32_16x16x32_bf16 v[64:67], v[182:185], v[214:217], v[64:67]
	s_barrier
	s_add_u32 s98, s26, s10
	s_addc_u32 s99, s27, s11
	s_add_u32 s100, s28, s10
	s_addc_u32 s101, s29, s11
	s_add_i32 s59, s47, s0
	s_mov_b32 m0, s59
	ds_read_b128 v[186:189], v156 offset:16384
	global_load_lds_dwordx4 v132, s[26:27]
	s_add_i32 m0, s59, 0x2000
	s_add_u32 s60, s26, 0x40000
	s_addc_u32 s61, s27, 0
	s_add_i32 s59, s48, s0
	global_load_lds_dwordx4 v128, s[26:27]
	s_mov_b32 m0, s59
	ds_read_b128 v[190:193], v156 offset:17408
	global_load_lds_dwordx4 v132, s[60:61]
	s_add_i32 m0, s59, 0x2000
	ds_read_b128 v[194:197], v156 offset:18432
	global_load_lds_dwordx4 v128, s[60:61]
	s_mov_b32 m0, s23
	ds_read_b128 v[198:201], v156 offset:19456
	global_load_lds_dwordx4 v134, s[28:29]
	s_mov_b32 m0, s37
	ds_read_b128 v[202:205], v156 offset:20480
	global_load_lds_dwordx4 v130, s[28:29]
	ds_read_b128 v[206:209], v156 offset:21504
	ds_read_b128 v[210:213], v156 offset:22528
	ds_read_b128 v[214:217], v156 offset:23552
	s_waitcnt vmcnt(8)
	s_waitcnt lgkmcnt(0)
	s_barrier
	v_mfma_f32_16x16x32_bf16 v[60:63], v[144:147], v[186:189], v[60:63]
	v_mfma_f32_16x16x32_bf16 v[56:59], v[162:165], v[186:189], v[56:59]
	v_mfma_f32_16x16x32_bf16 v[44:47], v[144:147], v[194:197], v[44:47]
	v_mfma_f32_16x16x32_bf16 v[40:43], v[162:165], v[194:197], v[40:43]
	v_mfma_f32_16x16x32_bf16 v[28:31], v[144:147], v[202:205], v[28:31]
	v_mfma_f32_16x16x32_bf16 v[24:27], v[162:165], v[202:205], v[24:27]
	v_mfma_f32_16x16x32_bf16 v[12:15], v[144:147], v[210:213], v[12:15]
	v_mfma_f32_16x16x32_bf16 v[8:11], v[162:165], v[210:213], v[8:11]
	v_mfma_f32_16x16x32_bf16 v[60:63], v[158:161], v[190:193], v[60:63]
	v_mfma_f32_16x16x32_bf16 v[56:59], v[166:169], v[190:193], v[56:59]
	v_mfma_f32_16x16x32_bf16 v[44:47], v[158:161], v[198:201], v[44:47]
	v_mfma_f32_16x16x32_bf16 v[40:43], v[166:169], v[198:201], v[40:43]
	v_mfma_f32_16x16x32_bf16 v[28:31], v[158:161], v[206:209], v[28:31]
	v_mfma_f32_16x16x32_bf16 v[24:27], v[166:169], v[206:209], v[24:27]
	v_mfma_f32_16x16x32_bf16 v[12:15], v[158:161], v[214:217], v[12:15]
	v_mfma_f32_16x16x32_bf16 v[8:11], v[166:169], v[214:217], v[8:11]
	v_mfma_f32_16x16x32_bf16 v[52:55], v[170:173], v[186:189], v[52:55]
	v_mfma_f32_16x16x32_bf16 v[48:51], v[178:181], v[186:189], v[48:51]
	v_mfma_f32_16x16x32_bf16 v[36:39], v[170:173], v[194:197], v[36:39]
	v_mfma_f32_16x16x32_bf16 v[32:35], v[178:181], v[194:197], v[32:35]
	v_mfma_f32_16x16x32_bf16 v[20:23], v[170:173], v[202:205], v[20:23]
	v_mfma_f32_16x16x32_bf16 v[16:19], v[178:181], v[202:205], v[16:19]
	v_mfma_f32_16x16x32_bf16 v[4:7], v[170:173], v[210:213], v[4:7]
	v_mfma_f32_16x16x32_bf16 v[0:3], v[178:181], v[210:213], v[0:3]
	v_mfma_f32_16x16x32_bf16 v[52:55], v[174:177], v[190:193], v[52:55]
	v_mfma_f32_16x16x32_bf16 v[48:51], v[182:185], v[190:193], v[48:51]
	v_mfma_f32_16x16x32_bf16 v[36:39], v[174:177], v[198:201], v[36:39]
	v_mfma_f32_16x16x32_bf16 v[32:35], v[182:185], v[198:201], v[32:35]
	v_mfma_f32_16x16x32_bf16 v[20:23], v[174:177], v[206:209], v[20:23]
	v_mfma_f32_16x16x32_bf16 v[16:19], v[182:185], v[206:209], v[16:19]
	v_mfma_f32_16x16x32_bf16 v[4:7], v[174:177], v[214:217], v[4:7]
	v_mfma_f32_16x16x32_bf16 v[0:3], v[182:185], v[214:217], v[0:3]
	s_barrier
; #define PG8_STAGE(bufoff, gbase, voff) do { _Pragma("unroll") for (int _i = 0; _i < 2; ++_i) \
;         __builtin_amdgcn_global_load_lds((const unsigned*)((const char*)(gbase) + (voff)[_i]), (PG8_LAS unsigned*)(lds + (bufoff) + ldsw + _i * 8192), 16, 0, 0); } while (0)
; #define PG8_LDA(dst, b, h) do { _Pragma("unroll") for (int m = 0; m < 4; ++m) _Pragma("unroll") for (int k = 0; k < 2; ++k) dst[m][k] = *(const PG8_LAS bf16x8*)(lds + PG8_SA(b, h) + aoff + m * 2048 + k * 1024); } while (0)
; #define PG8_WAIT_V(n) asm volatile("s_waitcnt vmcnt(" #n ")" ::: "memory")
; template <class Epi, class Sched, bool ALIGN_EPI = false, bool SP2 = false>
; __device__ __forceinline__ void gemm_phase(PG8_LAS unsigned char* lds, const Gemm g, const Sched& S, const Epi& E, int tid_in) {
;     ...
;         for (int t = 0; t < nt; t += 2) {
;             if constexpr (Epi::MIDK) { if (t == Epi::MIDK_T) { if (wr == 0) PG8_BAR; E.mid(acc, cur, wr, wc, fr, fq); if (wr == 1) PG8_BAR; } }
;             const bool last = (t == nt - 2);
;             const char* a1 = cA + (size_t)(t + 1) * kstep;
;             const char* a2 = last ? nA : cA + (size_t)(t + 2) * kstep; const char* b2 = last ? nB : cB + (size_t)(t + 2) * kstep;
;             const char* a3 = a2 + kstep; const char* b3 = b2 + kstep;
;             if (last && has_next) S.a_ready(nxt);
;             if constexpr (SP2) {
;             PG8_LDB(B0, 0, 0); PG8_LDB(B1, 0, 1); PG8_SCHED; PG8_LDA(At, 0, 0); PG8_STAGE(PG8_SA(1, 1), a1 + hstep, voffA);
;             PG8_WAIT_V(8); PG8_WAIT_L(0); PG8_BAR; PG8_MMA(0, 0, At, B0); PG8_MMA(0, 1, At, B1); PG8_BAR; PG8_SCHED;
;             PG8_LDA(At, 0, 1); PG8_STAGE(PG8_SB(0, 0), b2, voffB); PG8_STAGE(PG8_SB(0, 1), b2 + hstep, voffB); PG8_STAGE(PG8_SA(0, 0), a2, voffA);
;             PG8_WAIT_V(8); PG8_WAIT_L(0); PG8_BAR; PG8_MMA(1, 0, At, B0); PG8_MMA(1, 1, At, B1); PG8_BAR; PG8_SCHED;
;             PG8_LDB(B0, 1, 0); PG8_LDB(B1, 1, 1); PG8_SCHED; PG8_LDA(At, 1, 0); PG8_STAGE(PG8_SA(0, 1), a2 + hstep, voffA);
;             PG8_WAIT_V(8); PG8_WAIT_L(0); PG8_BAR; PG8_MMA(0, 0, At, B0); PG8_MMA(0, 1, At, B1); PG8_BAR; PG8_SCHED;
;             PG8_LDA(At, 1, 1); PG8_STAGE(PG8_SB(1, 0), b3, voffB); PG8_STAGE(PG8_SB(1, 1), b3 + hstep, voffB); PG8_STAGE(PG8_SA(1, 0), a3, voffA);
;             PG8_WAIT_V(8); PG8_WAIT_L(0); PG8_BAR; PG8_MMA(1, 0, At, B0); PG8_MMA(1, 1, At, B1); PG8_BAR; PG8_SCHED;
	s_add_i32 s59, 0, 0x18000
	s_add_i32 s60, 0, 0x1c000
	s_add_u32 s28, s28, 0x40000
	s_addc_u32 s29, s29, 0
	s_mov_b32 m0, s38
	v_add_u32_e32 v157, s59, v151
	global_load_lds_dwordx4 v134, s[28:29]
	s_mov_b32 m0, s39
	ds_read_b128 v[144:147], v157
	global_load_lds_dwordx4 v130, s[28:29]
	ds_read_b128 v[158:161], v157 offset:1024
	ds_read_b128 v[162:165], v157 offset:2048
	ds_read_b128 v[166:169], v157 offset:3072
	v_add_u32_e32 v157, s60, v151
	ds_read_b128 v[170:173], v157
	ds_read_b128 v[174:177], v157 offset:1024
	ds_read_b128 v[178:181], v157 offset:2048
	ds_read_b128 v[182:185], v157 offset:3072
	ds_read_b128 v[186:189], v156 offset:32768
	ds_read_b128 v[190:193], v156 offset:33792
	ds_read_b128 v[194:197], v156 offset:34816
	ds_read_b128 v[198:201], v156 offset:35840
	ds_read_b128 v[202:205], v156 offset:36864
	ds_read_b128 v[206:209], v156 offset:37888
	ds_read_b128 v[210:213], v156 offset:38912
	ds_read_b128 v[214:217], v156 offset:39936
	s_waitcnt vmcnt(8)
	s_waitcnt lgkmcnt(0)
	s_barrier
	v_mfma_f32_16x16x32_bf16 v[124:127], v[144:147], v[186:189], v[124:127]
	v_mfma_f32_16x16x32_bf16 v[120:123], v[162:165], v[186:189], v[120:123]
	v_mfma_f32_16x16x32_bf16 v[108:111], v[144:147], v[194:197], v[108:111]
	v_mfma_f32_16x16x32_bf16 v[104:107], v[162:165], v[194:197], v[104:107]
	v_mfma_f32_16x16x32_bf16 v[92:95], v[144:147], v[202:205], v[92:95]
	v_mfma_f32_16x16x32_bf16 v[88:91], v[162:165], v[202:205], v[88:91]
	v_mfma_f32_16x16x32_bf16 v[76:79], v[144:147], v[210:213], v[76:79]
	v_mfma_f32_16x16x32_bf16 v[72:75], v[162:165], v[210:213], v[72:75]
	v_mfma_f32_16x16x32_bf16 v[124:127], v[158:161], v[190:193], v[124:127]
	v_mfma_f32_16x16x32_bf16 v[120:123], v[166:169], v[190:193], v[120:123]
	v_mfma_f32_16x16x32_bf16 v[108:111], v[158:161], v[198:201], v[108:111]
	v_mfma_f32_16x16x32_bf16 v[104:107], v[166:169], v[198:201], v[104:107]
	v_mfma_f32_16x16x32_bf16 v[92:95], v[158:161], v[206:209], v[92:95]
	v_mfma_f32_16x16x32_bf16 v[88:91], v[166:169], v[206:209], v[88:91]
	v_mfma_f32_16x16x32_bf16 v[76:79], v[158:161], v[214:217], v[76:79]
	v_mfma_f32_16x16x32_bf16 v[72:75], v[166:169], v[214:217], v[72:75]
	v_mfma_f32_16x16x32_bf16 v[116:119], v[170:173], v[186:189], v[116:119]
	v_mfma_f32_16x16x32_bf16 v[112:115], v[178:181], v[186:189], v[112:115]
	v_mfma_f32_16x16x32_bf16 v[100:103], v[170:173], v[194:197], v[100:103]
	v_mfma_f32_16x16x32_bf16 v[96:99], v[178:181], v[194:197], v[96:99]
	v_mfma_f32_16x16x32_bf16 v[84:87], v[170:173], v[202:205], v[84:87]
	v_mfma_f32_16x16x32_bf16 v[80:83], v[178:181], v[202:205], v[80:83]
	v_mfma_f32_16x16x32_bf16 v[68:71], v[170:173], v[210:213], v[68:71]
	v_mfma_f32_16x16x32_bf16 v[64:67], v[178:181], v[210:213], v[64:67]
	v_mfma_f32_16x16x32_bf16 v[116:119], v[174:177], v[190:193], v[116:119]
	v_mfma_f32_16x16x32_bf16 v[112:115], v[182:185], v[190:193], v[112:115]
	v_mfma_f32_16x16x32_bf16 v[100:103], v[174:177], v[198:201], v[100:103]
	v_mfma_f32_16x16x32_bf16 v[96:99], v[182:185], v[198:201], v[96:99]
	v_mfma_f32_16x16x32_bf16 v[84:87], v[174:177], v[206:209], v[84:87]
	v_mfma_f32_16x16x32_bf16 v[80:83], v[182:185], v[206:209], v[80:83]
	v_mfma_f32_16x16x32_bf16 v[68:71], v[174:177], v[214:217], v[68:71]
	v_mfma_f32_16x16x32_bf16 v[64:67], v[182:185], v[214:217], v[64:67]
	s_barrier
	s_add_i32 s28, s59, s0
	s_mov_b32 m0, s28
	ds_read_b128 v[186:189], v156 offset:49152
	global_load_lds_dwordx4 v132, s[98:99]
	s_add_i32 m0, s28, 0x2000
	s_add_u32 s26, s26, 0x40080
	s_addc_u32 s27, s27, 0
	s_add_i32 s28, s60, s0
	global_load_lds_dwordx4 v128, s[98:99]
	s_mov_b32 m0, s28
	ds_read_b128 v[190:193], v156 offset:50176
	global_load_lds_dwordx4 v132, s[26:27]
	s_add_i32 m0, s28, 0x2000
	ds_read_b128 v[194:197], v156 offset:51200
	global_load_lds_dwordx4 v128, s[26:27]
	s_mov_b32 m0, s44
	ds_read_b128 v[198:201], v156 offset:52224
	global_load_lds_dwordx4 v134, s[100:101]
	s_mov_b32 m0, s45
	ds_read_b128 v[202:205], v156 offset:53248
	global_load_lds_dwordx4 v130, s[100:101]
	ds_read_b128 v[206:209], v156 offset:54272
	ds_read_b128 v[210:213], v156 offset:55296
	ds_read_b128 v[214:217], v156 offset:56320
	s_waitcnt vmcnt(8)
	s_waitcnt lgkmcnt(0)
	s_barrier
	v_mfma_f32_16x16x32_bf16 v[60:63], v[144:147], v[186:189], v[60:63]
	v_mfma_f32_16x16x32_bf16 v[56:59], v[162:165], v[186:189], v[56:59]
	v_mfma_f32_16x16x32_bf16 v[44:47], v[144:147], v[194:197], v[44:47]
	v_mfma_f32_16x16x32_bf16 v[40:43], v[162:165], v[194:197], v[40:43]
	v_mfma_f32_16x16x32_bf16 v[28:31], v[144:147], v[202:205], v[28:31]
	v_mfma_f32_16x16x32_bf16 v[24:27], v[162:165], v[202:205], v[24:27]
	v_mfma_f32_16x16x32_bf16 v[12:15], v[144:147], v[210:213], v[12:15]
	v_mfma_f32_16x16x32_bf16 v[8:11], v[162:165], v[210:213], v[8:11]
	v_mfma_f32_16x16x32_bf16 v[60:63], v[158:161], v[190:193], v[60:63]
	v_mfma_f32_16x16x32_bf16 v[56:59], v[166:169], v[190:193], v[56:59]
	v_mfma_f32_16x16x32_bf16 v[44:47], v[158:161], v[198:201], v[44:47]
	v_mfma_f32_16x16x32_bf16 v[40:43], v[166:169], v[198:201], v[40:43]
	v_mfma_f32_16x16x32_bf16 v[28:31], v[158:161], v[206:209], v[28:31]
	v_mfma_f32_16x16x32_bf16 v[24:27], v[166:169], v[206:209], v[24:27]
	v_mfma_f32_16x16x32_bf16 v[12:15], v[158:161], v[214:217], v[12:15]
	v_mfma_f32_16x16x32_bf16 v[8:11], v[166:169], v[214:217], v[8:11]
	v_mfma_f32_16x16x32_bf16 v[52:55], v[170:173], v[186:189], v[52:55]
	v_mfma_f32_16x16x32_bf16 v[48:51], v[178:181], v[186:189], v[48:51]
	v_mfma_f32_16x16x32_bf16 v[36:39], v[170:173], v[194:197], v[36:39]
	v_mfma_f32_16x16x32_bf16 v[32:35], v[178:181], v[194:197], v[32:35]
	v_mfma_f32_16x16x32_bf16 v[20:23], v[170:173], v[202:205], v[20:23]
	v_mfma_f32_16x16x32_bf16 v[16:19], v[178:181], v[202:205], v[16:19]
	v_mfma_f32_16x16x32_bf16 v[4:7], v[170:173], v[210:213], v[4:7]
	v_mfma_f32_16x16x32_bf16 v[0:3], v[178:181], v[210:213], v[0:3]
	v_mfma_f32_16x16x32_bf16 v[52:55], v[174:177], v[190:193], v[52:55]
	v_mfma_f32_16x16x32_bf16 v[48:51], v[182:185], v[190:193], v[48:51]
	v_mfma_f32_16x16x32_bf16 v[36:39], v[174:177], v[198:201], v[36:39]
	v_mfma_f32_16x16x32_bf16 v[32:35], v[182:185], v[198:201], v[32:35]
	v_mfma_f32_16x16x32_bf16 v[20:23], v[174:177], v[206:209], v[20:23]
	v_mfma_f32_16x16x32_bf16 v[16:19], v[182:185], v[206:209], v[16:19]
	v_mfma_f32_16x16x32_bf16 v[4:7], v[174:177], v[214:217], v[4:7]
	v_mfma_f32_16x16x32_bf16 v[0:3], v[182:185], v[214:217], v[0:3]
	s_barrier
	s_add_i32 s58, s58, 2
	s_add_u32 s24, s24, 0x100
	s_addc_u32 s25, s25, 0
	s_add_u32 s56, s56, 0x100
	s_addc_u32 s57, s57, 0
	s_cmp_gt_u32 s58, 13
	s_cbranch_scc0 .LBB0_1238
	s_and_b64 vcc, exec, s[12:13]
	s_cbranch_vccz .LBB0_1241
	s_barrier

; #define PG8_STAGE(bufoff, gbase, voff) do { _Pragma("unroll") for (int _i = 0; _i < 2; ++_i) \
;         __builtin_amdgcn_global_load_lds((const unsigned*)((const char*)(gbase) + (voff)[_i]), (PG8_LAS unsigned*)(lds + (bufoff) + ldsw + _i * 8192), 16, 0, 0); } while (0)
; #define PG8_LDA(dst, b, h) do { _Pragma("unroll") for (int m = 0; m < 4; ++m) _Pragma("unroll") for (int k = 0; k < 2; ++k) dst[m][k] = *(const PG8_LAS bf16x8*)(lds + PG8_SA(b, h) + aoff + m * 2048 + k * 1024); } while (0)
; #define PG8_LDB(dst, b, h) do { _Pragma("unroll") for (int n = 0; n < 2; ++n) _Pragma("unroll") for (int k = 0; k < 2; ++k) dst[n][k] = *(const PG8_LAS bf16x8*)(lds + PG8_SB(b, h) + boff + n * 2048 + k * 1024); } while (0)
; #define PG8_WAIT_V(n) asm volatile("s_waitcnt vmcnt(" #n ")" ::: "memory")
; template <class Epi, class Sched, bool ALIGN_EPI = false, bool SP2 = false>
; __device__ __forceinline__ void gemm_phase(PG8_LAS unsigned char* lds, const Gemm g, const Sched& S, const Epi& E, int tid_in) {
;     ...
;             const char* a1 = cA + (size_t)(t + 1) * kstep;
;             const char* a2 = last ? nA : cA + (size_t)(t + 2) * kstep; const char* b2 = last ? nB : cB + (size_t)(t + 2) * kstep;
;             const char* a3 = a2 + kstep; const char* b3 = b2 + kstep;
;             if (last && has_next) S.a_ready(nxt);
;             if constexpr (SP2) {
;             PG8_LDB(B0, 0, 0); PG8_LDB(B1, 0, 1); PG8_SCHED; PG8_LDA(At, 0, 0); PG8_STAGE(PG8_SA(1, 1), a1 + hstep, voffA);
;             PG8_WAIT_V(8); PG8_WAIT_L(0); PG8_BAR; PG8_MMA(0, 0, At, B0); PG8_MMA(0, 1, At, B1); PG8_BAR; PG8_SCHED;
;             PG8_LDA(At, 0, 1); PG8_STAGE(PG8_SB(0, 0), b2, voffB); PG8_STAGE(PG8_SB(0, 1), b2 + hstep, voffB); PG8_STAGE(PG8_SA(0, 0), a2, voffA);
;             PG8_WAIT_V(8); PG8_WAIT_L(0); PG8_BAR; PG8_MMA(1, 0, At, B0); PG8_MMA(1, 1, At, B1); PG8_BAR; PG8_SCHED;
;             PG8_LDB(B0, 1, 0); PG8_LDB(B1, 1, 1); PG8_SCHED; PG8_LDA(At, 1, 0); PG8_STAGE(PG8_SA(0, 1), a2 + hstep, voffA);
;             PG8_WAIT_V(8); PG8_WAIT_L(0); PG8_BAR; PG8_MMA(0, 0, At, B0); PG8_MMA(0, 1, At, B1); PG8_BAR; PG8_SCHED;
;             PG8_LDA(At, 1, 1); PG8_STAGE(PG8_SB(1, 0), b3, voffB); PG8_STAGE(PG8_SB(1, 1), b3 + hstep, voffB); PG8_STAGE(PG8_SA(1, 0), a3, voffA);
;             PG8_WAIT_V(8); PG8_WAIT_L(0); PG8_BAR; PG8_MMA(1, 0, At, B0); PG8_MMA(1, 1, At, B1); PG8_BAR; PG8_SCHED;
.LBB0_1321:
	s_add_u32 s2, s20, 0x100
	s_addc_u32 s3, s21, 0
	s_cmp_eq_u32 s50, 40
	s_cselect_b32 s25, s17, s3
	s_cselect_b32 s24, s16, s2
	s_cselect_b32 s23, s19, s49
	s_cselect_b32 s22, s18, s48
	s_add_i32 m0, s34, 0xc000
	ds_read_b128 v[128:131], v195
	global_load_lds_dwordx4 v168, s[20:21]
	s_add_i32 m0, s34, 0xe000
	ds_read_b128 v[132:135], v195 offset:1024
	global_load_lds_dwordx4 v170, s[20:21]
	ds_read_b128 v[136:139], v195 offset:2048
	ds_read_b128 v[140:143], v195 offset:3072
	ds_read_b128 v[144:147], v196
	ds_read_b128 v[148:151], v196 offset:1024
	ds_read_b128 v[152:155], v196 offset:2048
	ds_read_b128 v[156:159], v196 offset:3072
	ds_read_b128 v[176:179], v197
	ds_read_b128 v[180:183], v197 offset:1024
	ds_read_b128 v[184:187], v197 offset:2048
	ds_read_b128 v[188:191], v197 offset:3072
	ds_read_b128 v[198:201], v197 offset:4096
	ds_read_b128 v[202:205], v197 offset:5120
	ds_read_b128 v[206:209], v197 offset:6144
	ds_read_b128 v[210:213], v197 offset:7168
	s_waitcnt vmcnt(8)
	s_waitcnt lgkmcnt(0)
	s_barrier
	v_mfma_f32_16x16x32_bf16 v[120:123], v[128:131], v[176:179], v[120:123]
	v_mfma_f32_16x16x32_bf16 v[124:127], v[136:139], v[176:179], v[124:127]
	v_mfma_f32_16x16x32_bf16 v[104:107], v[128:131], v[184:187], v[104:107]
	v_mfma_f32_16x16x32_bf16 v[108:111], v[136:139], v[184:187], v[108:111]
	v_mfma_f32_16x16x32_bf16 v[88:91], v[128:131], v[198:201], v[88:91]
	v_mfma_f32_16x16x32_bf16 v[92:95], v[136:139], v[198:201], v[92:95]
	v_mfma_f32_16x16x32_bf16 v[72:75], v[128:131], v[206:209], v[72:75]
	v_mfma_f32_16x16x32_bf16 v[76:79], v[136:139], v[206:209], v[76:79]
	v_mfma_f32_16x16x32_bf16 v[120:123], v[132:135], v[180:183], v[120:123]
	v_mfma_f32_16x16x32_bf16 v[124:127], v[140:143], v[180:183], v[124:127]
	v_mfma_f32_16x16x32_bf16 v[104:107], v[132:135], v[188:191], v[104:107]
	v_mfma_f32_16x16x32_bf16 v[108:111], v[140:143], v[188:191], v[108:111]
	v_mfma_f32_16x16x32_bf16 v[88:91], v[132:135], v[202:205], v[88:91]
	v_mfma_f32_16x16x32_bf16 v[92:95], v[140:143], v[202:205], v[92:95]
	v_mfma_f32_16x16x32_bf16 v[72:75], v[132:135], v[210:213], v[72:75]
	v_mfma_f32_16x16x32_bf16 v[76:79], v[140:143], v[210:213], v[76:79]
	v_mfma_f32_16x16x32_bf16 v[112:115], v[144:147], v[176:179], v[112:115]
	v_mfma_f32_16x16x32_bf16 v[116:119], v[152:155], v[176:179], v[116:119]
	v_mfma_f32_16x16x32_bf16 v[96:99], v[144:147], v[184:187], v[96:99]
	v_mfma_f32_16x16x32_bf16 v[100:103], v[152:155], v[184:187], v[100:103]
	v_mfma_f32_16x16x32_bf16 v[80:83], v[144:147], v[198:201], v[80:83]
	v_mfma_f32_16x16x32_bf16 v[84:87], v[152:155], v[198:201], v[84:87]
	v_mfma_f32_16x16x32_bf16 v[64:67], v[144:147], v[206:209], v[64:67]
	v_mfma_f32_16x16x32_bf16 v[68:71], v[152:155], v[206:209], v[68:71]
	v_mfma_f32_16x16x32_bf16 v[112:115], v[148:151], v[180:183], v[112:115]
	v_mfma_f32_16x16x32_bf16 v[116:119], v[156:159], v[180:183], v[116:119]
	v_mfma_f32_16x16x32_bf16 v[96:99], v[148:151], v[188:191], v[96:99]
	v_mfma_f32_16x16x32_bf16 v[100:103], v[156:159], v[188:191], v[100:103]
	v_mfma_f32_16x16x32_bf16 v[80:83], v[148:151], v[202:205], v[80:83]
	v_mfma_f32_16x16x32_bf16 v[84:87], v[156:159], v[202:205], v[84:87]
	v_mfma_f32_16x16x32_bf16 v[64:67], v[148:151], v[210:213], v[64:67]
	v_mfma_f32_16x16x32_bf16 v[68:71], v[156:159], v[210:213], v[68:71]
	s_barrier
	s_add_u32 s98, s22, s10
	s_addc_u32 s99, s23, s11
	s_add_u32 s100, s24, s10
	s_addc_u32 s101, s25, s11
	s_add_i32 s20, s42, s31
	s_mov_b32 m0, s20
	ds_read_b128 v[176:179], v197 offset:16384
	global_load_lds_dwordx4 v162, s[22:23]
	s_add_i32 m0, s20, 0x2000
	s_add_u32 s20, s22, 0xb0000
	s_addc_u32 s21, s23, 0
	s_add_i32 s51, s43, s31
	global_load_lds_dwordx4 v166, s[22:23]
	s_mov_b32 m0, s51
	ds_read_b128 v[180:183], v197 offset:17408
	global_load_lds_dwordx4 v162, s[20:21]
	s_add_i32 m0, s51, 0x2000
	ds_read_b128 v[184:187], v197 offset:18432
	global_load_lds_dwordx4 v166, s[20:21]
	s_mov_b32 m0, s34
	ds_read_b128 v[188:191], v197 offset:19456
	global_load_lds_dwordx4 v160, s[24:25]
	s_mov_b32 m0, s35
	ds_read_b128 v[198:201], v197 offset:20480
	global_load_lds_dwordx4 v164, s[24:25]
	ds_read_b128 v[202:205], v197 offset:21504
	ds_read_b128 v[206:209], v197 offset:22528
	ds_read_b128 v[210:213], v197 offset:23552
	s_waitcnt vmcnt(8)
	s_waitcnt lgkmcnt(0)
	s_barrier
	v_mfma_f32_16x16x32_bf16 v[56:59], v[128:131], v[176:179], v[56:59]
	v_mfma_f32_16x16x32_bf16 v[60:63], v[136:139], v[176:179], v[60:63]
	v_mfma_f32_16x16x32_bf16 v[40:43], v[128:131], v[184:187], v[40:43]
	v_mfma_f32_16x16x32_bf16 v[44:47], v[136:139], v[184:187], v[44:47]
	v_mfma_f32_16x16x32_bf16 v[24:27], v[128:131], v[198:201], v[24:27]
	v_mfma_f32_16x16x32_bf16 v[28:31], v[136:139], v[198:201], v[28:31]
	v_mfma_f32_16x16x32_bf16 v[8:11], v[128:131], v[206:209], v[8:11]
	v_mfma_f32_16x16x32_bf16 v[12:15], v[136:139], v[206:209], v[12:15]
	v_mfma_f32_16x16x32_bf16 v[56:59], v[132:135], v[180:183], v[56:59]
	v_mfma_f32_16x16x32_bf16 v[60:63], v[140:143], v[180:183], v[60:63]
	v_mfma_f32_16x16x32_bf16 v[40:43], v[132:135], v[188:191], v[40:43]
	v_mfma_f32_16x16x32_bf16 v[44:47], v[140:143], v[188:191], v[44:47]
	v_mfma_f32_16x16x32_bf16 v[24:27], v[132:135], v[202:205], v[24:27]
	v_mfma_f32_16x16x32_bf16 v[28:31], v[140:143], v[202:205], v[28:31]
	v_mfma_f32_16x16x32_bf16 v[8:11], v[132:135], v[210:213], v[8:11]
	v_mfma_f32_16x16x32_bf16 v[12:15], v[140:143], v[210:213], v[12:15]
	v_mfma_f32_16x16x32_bf16 v[48:51], v[144:147], v[176:179], v[48:51]
	v_mfma_f32_16x16x32_bf16 v[52:55], v[152:155], v[176:179], v[52:55]
	v_mfma_f32_16x16x32_bf16 v[32:35], v[144:147], v[184:187], v[32:35]
	v_mfma_f32_16x16x32_bf16 v[36:39], v[152:155], v[184:187], v[36:39]
	v_mfma_f32_16x16x32_bf16 v[16:19], v[144:147], v[198:201], v[16:19]
	v_mfma_f32_16x16x32_bf16 v[20:23], v[152:155], v[198:201], v[20:23]
	v_mfma_f32_16x16x32_bf16 v[4:7], v[144:147], v[206:209], v[4:7]
	v_mfma_f32_16x16x32_bf16 v[0:3], v[152:155], v[206:209], v[0:3]
	v_mfma_f32_16x16x32_bf16 v[48:51], v[148:151], v[180:183], v[48:51]
	v_mfma_f32_16x16x32_bf16 v[52:55], v[156:159], v[180:183], v[52:55]
	v_mfma_f32_16x16x32_bf16 v[32:35], v[148:151], v[188:191], v[32:35]
	v_mfma_f32_16x16x32_bf16 v[36:39], v[156:159], v[188:191], v[36:39]
	v_mfma_f32_16x16x32_bf16 v[16:19], v[148:151], v[202:205], v[16:19]
	v_mfma_f32_16x16x32_bf16 v[20:23], v[156:159], v[202:205], v[20:23]
	v_mfma_f32_16x16x32_bf16 v[4:7], v[148:151], v[210:213], v[4:7]
	v_mfma_f32_16x16x32_bf16 v[0:3], v[156:159], v[210:213], v[0:3]
	s_barrier
; #define PG8_STAGE(bufoff, gbase, voff) do { _Pragma("unroll") for (int _i = 0; _i < 2; ++_i) \
;         __builtin_amdgcn_global_load_lds((const unsigned*)((const char*)(gbase) + (voff)[_i]), (PG8_LAS unsigned*)(lds + (bufoff) + ldsw + _i * 8192), 16, 0, 0); } while (0)
; #define PG8_LDA(dst, b, h) do { _Pragma("unroll") for (int m = 0; m < 4; ++m) _Pragma("unroll") for (int k = 0; k < 2; ++k) dst[m][k] = *(const PG8_LAS bf16x8*)(lds + PG8_SA(b, h) + aoff + m * 2048 + k * 1024); } while (0)
; #define PG8_WAIT_V(n) asm volatile("s_waitcnt vmcnt(" #n ")" ::: "memory")
; template <class Epi, class Sched, bool ALIGN_EPI = false, bool SP2 = false>
; __device__ __forceinline__ void gemm_phase(PG8_LAS unsigned char* lds, const Gemm g, const Sched& S, const Epi& E, int tid_in) {
;     ...
;         for (int t = 0; t < nt; t += 2) {
;             if constexpr (Epi::MIDK) { if (t == Epi::MIDK_T) { if (wr == 0) PG8_BAR; E.mid(acc, cur, wr, wc, fr, fq); if (wr == 1) PG8_BAR; } }
;             const bool last = (t == nt - 2);
;             const char* a1 = cA + (size_t)(t + 1) * kstep;
;             const char* a2 = last ? nA : cA + (size_t)(t + 2) * kstep; const char* b2 = last ? nB : cB + (size_t)(t + 2) * kstep;
;             const char* a3 = a2 + kstep; const char* b3 = b2 + kstep;
;             if (last && has_next) S.a_ready(nxt);
;             if constexpr (SP2) {
;             PG8_LDB(B0, 0, 0); PG8_LDB(B1, 0, 1); PG8_SCHED; PG8_LDA(At, 0, 0); PG8_STAGE(PG8_SA(1, 1), a1 + hstep, voffA);
;             PG8_WAIT_V(8); PG8_WAIT_L(0); PG8_BAR; PG8_MMA(0, 0, At, B0); PG8_MMA(0, 1, At, B1); PG8_BAR; PG8_SCHED;
;             PG8_LDA(At, 0, 1); PG8_STAGE(PG8_SB(0, 0), b2, voffB); PG8_STAGE(PG8_SB(0, 1), b2 + hstep, voffB); PG8_STAGE(PG8_SA(0, 0), a2, voffA);
;             PG8_WAIT_V(8); PG8_WAIT_L(0); PG8_BAR; PG8_MMA(1, 0, At, B0); PG8_MMA(1, 1, At, B1); PG8_BAR; PG8_SCHED;
;             PG8_LDB(B0, 1, 0); PG8_LDB(B1, 1, 1); PG8_SCHED; PG8_LDA(At, 1, 0); PG8_STAGE(PG8_SA(0, 1), a2 + hstep, voffA);
;             PG8_WAIT_V(8); PG8_WAIT_L(0); PG8_BAR; PG8_MMA(0, 0, At, B0); PG8_MMA(0, 1, At, B1); PG8_BAR; PG8_SCHED;
;             PG8_LDA(At, 1, 1); PG8_STAGE(PG8_SB(1, 0), b3, voffB); PG8_STAGE(PG8_SB(1, 1), b3 + hstep, voffB); PG8_STAGE(PG8_SA(1, 0), a3, voffA);
;             PG8_WAIT_V(8); PG8_WAIT_L(0); PG8_BAR; PG8_MMA(1, 0, At, B0); PG8_MMA(1, 1, At, B1); PG8_BAR; PG8_SCHED;
	s_add_i32 s51, 0, 0x18000
	s_add_i32 s52, 0, 0x1c000
	s_add_u32 s20, s24, 0xb0000
	s_addc_u32 s21, s25, 0
	s_mov_b32 m0, s36
	s_nop 0
	global_load_lds_dwordx4 v160, s[20:21]
	s_mov_b32 m0, s37
	s_nop 0
	global_load_lds_dwordx4 v164, s[20:21]
	v_add_u32_e32 v140, s51, v193
	v_add_u32_e32 v156, s52, v193
	ds_read_b128 v[128:131], v140
	ds_read_b128 v[132:135], v140 offset:1024
	ds_read_b128 v[136:139], v140 offset:2048
	ds_read_b128 v[140:143], v140 offset:3072
	ds_read_b128 v[144:147], v156
	ds_read_b128 v[148:151], v156 offset:1024
	ds_read_b128 v[152:155], v156 offset:2048
	ds_read_b128 v[156:159], v156 offset:3072
	ds_read_b128 v[176:179], v197 offset:32768
	ds_read_b128 v[180:183], v197 offset:33792
	ds_read_b128 v[184:187], v197 offset:34816
	ds_read_b128 v[188:191], v197 offset:35840
	ds_read_b128 v[198:201], v197 offset:36864
	ds_read_b128 v[202:205], v197 offset:37888
	ds_read_b128 v[206:209], v197 offset:38912
	ds_read_b128 v[210:213], v197 offset:39936
	s_waitcnt vmcnt(8)
	s_waitcnt lgkmcnt(0)
	s_barrier
	v_mfma_f32_16x16x32_bf16 v[120:123], v[128:131], v[176:179], v[120:123]
	v_mfma_f32_16x16x32_bf16 v[124:127], v[136:139], v[176:179], v[124:127]
	v_mfma_f32_16x16x32_bf16 v[104:107], v[128:131], v[184:187], v[104:107]
	v_mfma_f32_16x16x32_bf16 v[108:111], v[136:139], v[184:187], v[108:111]
	v_mfma_f32_16x16x32_bf16 v[88:91], v[128:131], v[198:201], v[88:91]
	v_mfma_f32_16x16x32_bf16 v[92:95], v[136:139], v[198:201], v[92:95]
	v_mfma_f32_16x16x32_bf16 v[72:75], v[128:131], v[206:209], v[72:75]
	v_mfma_f32_16x16x32_bf16 v[76:79], v[136:139], v[206:209], v[76:79]
	v_mfma_f32_16x16x32_bf16 v[120:123], v[132:135], v[180:183], v[120:123]
	v_mfma_f32_16x16x32_bf16 v[124:127], v[140:143], v[180:183], v[124:127]
	v_mfma_f32_16x16x32_bf16 v[104:107], v[132:135], v[188:191], v[104:107]
	v_mfma_f32_16x16x32_bf16 v[108:111], v[140:143], v[188:191], v[108:111]
	v_mfma_f32_16x16x32_bf16 v[88:91], v[132:135], v[202:205], v[88:91]
	v_mfma_f32_16x16x32_bf16 v[92:95], v[140:143], v[202:205], v[92:95]
	v_mfma_f32_16x16x32_bf16 v[72:75], v[132:135], v[210:213], v[72:75]
	v_mfma_f32_16x16x32_bf16 v[76:79], v[140:143], v[210:213], v[76:79]
	v_mfma_f32_16x16x32_bf16 v[112:115], v[144:147], v[176:179], v[112:115]
	v_mfma_f32_16x16x32_bf16 v[116:119], v[152:155], v[176:179], v[116:119]
	v_mfma_f32_16x16x32_bf16 v[96:99], v[144:147], v[184:187], v[96:99]
	v_mfma_f32_16x16x32_bf16 v[100:103], v[152:155], v[184:187], v[100:103]
	v_mfma_f32_16x16x32_bf16 v[80:83], v[144:147], v[198:201], v[80:83]
	v_mfma_f32_16x16x32_bf16 v[84:87], v[152:155], v[198:201], v[84:87]
	v_mfma_f32_16x16x32_bf16 v[64:67], v[144:147], v[206:209], v[64:67]
	v_mfma_f32_16x16x32_bf16 v[68:71], v[152:155], v[206:209], v[68:71]
	v_mfma_f32_16x16x32_bf16 v[112:115], v[148:151], v[180:183], v[112:115]
	v_mfma_f32_16x16x32_bf16 v[116:119], v[156:159], v[180:183], v[116:119]
	v_mfma_f32_16x16x32_bf16 v[96:99], v[148:151], v[188:191], v[96:99]
	v_mfma_f32_16x16x32_bf16 v[100:103], v[156:159], v[188:191], v[100:103]
	v_mfma_f32_16x16x32_bf16 v[80:83], v[148:151], v[202:205], v[80:83]
	v_mfma_f32_16x16x32_bf16 v[84:87], v[156:159], v[202:205], v[84:87]
	v_mfma_f32_16x16x32_bf16 v[64:67], v[148:151], v[210:213], v[64:67]
	v_mfma_f32_16x16x32_bf16 v[68:71], v[156:159], v[210:213], v[68:71]
	s_barrier
	s_add_i32 s20, s51, s31
	s_mov_b32 m0, s20
	ds_read_b128 v[176:179], v197 offset:49152
	global_load_lds_dwordx4 v162, s[98:99]
	s_add_i32 m0, s20, 0x2000
	s_add_u32 s20, s22, 0xb0080
	s_addc_u32 s21, s23, 0
	s_add_i32 s22, s52, s31
	global_load_lds_dwordx4 v166, s[98:99]
	s_mov_b32 m0, s22
	ds_read_b128 v[180:183], v197 offset:50176
	global_load_lds_dwordx4 v162, s[20:21]
	s_add_i32 m0, s22, 0x2000
	ds_read_b128 v[184:187], v197 offset:51200
	global_load_lds_dwordx4 v166, s[20:21]
	s_mov_b32 m0, s39
	ds_read_b128 v[188:191], v197 offset:52224
	global_load_lds_dwordx4 v160, s[100:101]
	s_mov_b32 m0, s40
	ds_read_b128 v[198:201], v197 offset:53248
	global_load_lds_dwordx4 v164, s[100:101]
	ds_read_b128 v[202:205], v197 offset:54272
	ds_read_b128 v[206:209], v197 offset:55296
	ds_read_b128 v[210:213], v197 offset:56320
	s_waitcnt vmcnt(8)
	s_waitcnt lgkmcnt(0)
	s_barrier
	v_mfma_f32_16x16x32_bf16 v[56:59], v[128:131], v[176:179], v[56:59]
	v_mfma_f32_16x16x32_bf16 v[60:63], v[136:139], v[176:179], v[60:63]
	v_mfma_f32_16x16x32_bf16 v[40:43], v[128:131], v[184:187], v[40:43]
	v_mfma_f32_16x16x32_bf16 v[44:47], v[136:139], v[184:187], v[44:47]
	v_mfma_f32_16x16x32_bf16 v[24:27], v[128:131], v[198:201], v[24:27]
	v_mfma_f32_16x16x32_bf16 v[28:31], v[136:139], v[198:201], v[28:31]
	v_mfma_f32_16x16x32_bf16 v[8:11], v[128:131], v[206:209], v[8:11]
	v_mfma_f32_16x16x32_bf16 v[12:15], v[136:139], v[206:209], v[12:15]
	v_mfma_f32_16x16x32_bf16 v[56:59], v[132:135], v[180:183], v[56:59]
	v_mfma_f32_16x16x32_bf16 v[60:63], v[140:143], v[180:183], v[60:63]
	v_mfma_f32_16x16x32_bf16 v[40:43], v[132:135], v[188:191], v[40:43]
	v_mfma_f32_16x16x32_bf16 v[44:47], v[140:143], v[188:191], v[44:47]
	v_mfma_f32_16x16x32_bf16 v[24:27], v[132:135], v[202:205], v[24:27]
	v_mfma_f32_16x16x32_bf16 v[28:31], v[140:143], v[202:205], v[28:31]
	v_mfma_f32_16x16x32_bf16 v[8:11], v[132:135], v[210:213], v[8:11]
	v_mfma_f32_16x16x32_bf16 v[12:15], v[140:143], v[210:213], v[12:15]
	v_mfma_f32_16x16x32_bf16 v[48:51], v[144:147], v[176:179], v[48:51]
	v_mfma_f32_16x16x32_bf16 v[52:55], v[152:155], v[176:179], v[52:55]
	v_mfma_f32_16x16x32_bf16 v[32:35], v[144:147], v[184:187], v[32:35]
	v_mfma_f32_16x16x32_bf16 v[36:39], v[152:155], v[184:187], v[36:39]
	v_mfma_f32_16x16x32_bf16 v[16:19], v[144:147], v[198:201], v[16:19]
	v_mfma_f32_16x16x32_bf16 v[20:23], v[152:155], v[198:201], v[20:23]
	v_mfma_f32_16x16x32_bf16 v[4:7], v[144:147], v[206:209], v[4:7]
	v_mfma_f32_16x16x32_bf16 v[0:3], v[152:155], v[206:209], v[0:3]
	v_mfma_f32_16x16x32_bf16 v[48:51], v[148:151], v[180:183], v[48:51]
	v_mfma_f32_16x16x32_bf16 v[52:55], v[156:159], v[180:183], v[52:55]
	v_mfma_f32_16x16x32_bf16 v[32:35], v[148:151], v[188:191], v[32:35]
	v_mfma_f32_16x16x32_bf16 v[36:39], v[156:159], v[188:191], v[36:39]
	v_mfma_f32_16x16x32_bf16 v[16:19], v[148:151], v[202:205], v[16:19]
	v_mfma_f32_16x16x32_bf16 v[20:23], v[156:159], v[202:205], v[20:23]
	v_mfma_f32_16x16x32_bf16 v[4:7], v[148:151], v[210:213], v[4:7]
	v_mfma_f32_16x16x32_bf16 v[0:3], v[156:159], v[210:213], v[0:3]
	s_barrier
	s_add_i32 s50, s50, 2
	s_add_u32 s48, s48, 0x100
	s_addc_u32 s49, s49, 0
	s_cmp_gt_u32 s50, 41
	s_mov_b64 s[20:21], s[2:3]
	s_cbranch_scc0 .LBB0_1321
	s_and_b64 vcc, exec, s[12:13]
	s_cbranch_vccz .LBB0_1324
	s_barrier
